# up epilogue: the two 8-byte ACT stores of each row block merged into one 16-byte store (n=0 half parked in dead accumulator registers)
# speedup vs baseline: 1.0076x; 1.0007x over previous
.LBB0_883:
	s_lshl_b64 s[2:3], s[2:3], 2
	s_add_u32 s1, s58, s2
	s_addc_u32 s9, s59, s3
	s_lshl_b32 s2, s0, 8
	s_ashr_i32 s3, s2, 31
	s_lshl_b64 s[2:3], s[2:3], 2
	s_add_u32 s1, s1, s2
	s_addc_u32 s3, s9, s3
	s_add_u32 s2, s1, s66
	s_addc_u32 s3, s3, 0
	s_lshl_b32 s1, s8, 8
	s_add_i32 s1, s1, s60
	s_lshl_b32 s84, s83, 7
	s_add_i32 s1, s1, s84
	v_add_u32_e32 v192, s1, v239
	v_ashrrev_i32_e32 v193, 31, v192
	v_lshl_add_u64 v[104:105], v[192:193], 2, s[22:23]
	global_load_dword v193, v[104:105], off
	global_load_dword v196, v[104:105], off offset:64
	s_lshl_b32 s0, s0, 7
	v_lshlrev_b32_e32 v106, 3, v48
	s_or_b32 s0, s0, s61
	v_add_u32_e32 v190, s0, v106
	v_ashrrev_i32_e32 v107, 31, v106
	v_ashrrev_i32_e32 v191, 31, v190
	v_lshl_add_u64 v[48:49], v[106:107], 2, s[2:3]
	v_lshlrev_b64 v[106:107], 2, v[190:191]
	global_load_dwordx4 v[120:123], v[48:49], off
	global_load_dwordx4 v[116:119], v[48:49], off offset:512
	global_load_dwordx4 v[52:55], v[48:49], off offset:16
	s_nop 0
	global_load_dwordx4 v[48:51], v[48:49], off offset:528
	s_nop 0
	global_load_dword v243, v[104:105], off offset:128
	global_load_dword v242, v[104:105], off offset:192
	global_load_dword v241, v[104:105], off offset:512
	global_load_dword v240, v[104:105], off offset:576
	global_load_dword v199, v[104:105], off offset:640
	global_load_dword v197, v[104:105], off offset:704
	v_lshl_add_u64 v[194:195], s[20:21], 0, v[106:107]
	v_lshl_add_u64 v[104:105], s[24:25], 0, v[106:107]
	v_lshl_add_u64 v[108:109], s[26:27], 0, v[106:107]
	v_lshl_add_u64 v[110:111], s[28:29], 0, v[106:107]
	v_lshl_add_u64 v[160:161], s[30:31], 0, v[106:107]
	v_lshl_add_u64 v[200:201], s[34:35], 0, v[106:107]
	global_load_dwordx4 v[220:223], v[194:195], off offset:16
	global_load_dwordx4 v[156:159], v[194:195], off
	s_nop 0
	global_load_dwordx4 v[204:207], v[104:105], off offset:16
	global_load_dwordx4 v[104:107], v[104:105], off
	s_nop 0
	global_load_dwordx4 v[208:211], v[108:109], off offset:16
	global_load_dwordx4 v[164:167], v[108:109], off
	global_load_dwordx4 v[212:215], v[110:111], off offset:16
	global_load_dwordx4 v[112:115], v[110:111], off
	s_nop 0
	global_load_dwordx4 v[216:219], v[160:161], off offset:16
	global_load_dwordx4 v[160:163], v[160:161], off
	s_nop 0
	global_load_dwordx4 v[108:111], v[200:201], off
	global_load_dwordx4 v[200:203], v[200:201], off offset:16
	v_cmp_ne_u32_e64 s[10:11], 0, v239
	v_cmp_ne_u32_e64 s[8:9], 15, v239
	v_cmp_gt_u32_e64 s[12:13], 2, v239
	v_cmp_lt_u32_e64 s[14:15], 13, v239
	s_mov_b32 s0, 0xbfb8aa3b
	s_mov_b32 s1, 0xbfb8aa3b
	s_mov_b64 s[2:3], 0x16000
	s_waitcnt vmcnt(0)
	v_fmamk_f32 v244, v193, 0x3a800000, v225
	v_fmamk_f32 v196, v196, 0x3a800000, v225
	v_fmamk_f32 v246, v243, 0x3a800000, v225
	v_fmamk_f32 v242, v242, 0x3a800000, v225
	v_fmamk_f32 v248, v241, 0x3a800000, v225
	v_fmamk_f32 v240, v240, 0x3a800000, v225
	v_fmamk_f32 v198, v199, 0x3a800000, v225
	v_fmamk_f32 v250, v197, 0x3a800000, v225
	v_rsq_f32_e32 v244, v244
	v_rsq_f32_e32 v196, v196
	v_rsq_f32_e32 v246, v246
	v_rsq_f32_e32 v242, v242
	v_rsq_f32_e32 v248, v248
	v_rsq_f32_e32 v240, v240
	v_rsq_f32_e32 v198, v198
	v_rsq_f32_e32 v250, v250
	v_pk_fma_f32 v[152:153], v[152:153], v[244:245], v[120:121] op_sel_hi:[1,0,1]
	v_pk_fma_f32 v[154:155], v[154:155], v[244:245], v[122:123] op_sel_hi:[1,0,1]
	v_pk_fma_f32 v[68:69], v[68:69], v[244:245], v[52:53] op_sel_hi:[1,0,1]
	v_pk_fma_f32 v[70:71], v[70:71], v[244:245], v[54:55] op_sel_hi:[1,0,1]
	v_pk_fma_f32 v[144:145], v[144:145], v[244:245], v[116:117] op_sel_hi:[1,0,1]
	v_pk_fma_f32 v[146:147], v[146:147], v[244:245], v[118:119] op_sel_hi:[1,0,1]
	v_pk_fma_f32 v[60:61], v[60:61], v[244:245], v[48:49] op_sel_hi:[1,0,1]
	v_pk_fma_f32 v[62:63], v[62:63], v[244:245], v[50:51] op_sel_hi:[1,0,1]
	v_pk_fma_f32 v[148:149], v[148:149], v[196:197], v[120:121] op_sel_hi:[1,0,1]
	v_pk_fma_f32 v[150:151], v[150:151], v[196:197], v[122:123] op_sel_hi:[1,0,1]
	v_pk_fma_f32 v[64:65], v[64:65], v[196:197], v[52:53] op_sel_hi:[1,0,1]
	v_pk_fma_f32 v[66:67], v[66:67], v[196:197], v[54:55] op_sel_hi:[1,0,1]
	v_pk_fma_f32 v[140:141], v[140:141], v[196:197], v[116:117] op_sel_hi:[1,0,1]
	v_pk_fma_f32 v[142:143], v[142:143], v[196:197], v[118:119] op_sel_hi:[1,0,1]
	v_pk_fma_f32 v[56:57], v[56:57], v[196:197], v[48:49] op_sel_hi:[1,0,1]
	v_pk_fma_f32 v[58:59], v[58:59], v[196:197], v[50:51] op_sel_hi:[1,0,1]
	v_pk_fma_f32 v[136:137], v[136:137], v[246:247], v[120:121] op_sel_hi:[1,0,1]
	v_pk_fma_f32 v[138:139], v[138:139], v[246:247], v[122:123] op_sel_hi:[1,0,1]
	v_pk_fma_f32 v[44:45], v[44:45], v[246:247], v[52:53] op_sel_hi:[1,0,1]
	v_pk_fma_f32 v[46:47], v[46:47], v[246:247], v[54:55] op_sel_hi:[1,0,1]
	v_pk_fma_f32 v[132:133], v[132:133], v[246:247], v[116:117] op_sel_hi:[1,0,1]
	v_pk_fma_f32 v[134:135], v[134:135], v[246:247], v[118:119] op_sel_hi:[1,0,1]
	v_pk_fma_f32 v[36:37], v[36:37], v[246:247], v[48:49] op_sel_hi:[1,0,1]
	v_pk_fma_f32 v[38:39], v[38:39], v[246:247], v[50:51] op_sel_hi:[1,0,1]
	v_pk_fma_f32 v[128:129], v[128:129], v[242:243], v[120:121] op_sel_hi:[1,0,1]
	v_pk_fma_f32 v[130:131], v[130:131], v[242:243], v[122:123] op_sel_hi:[1,0,1]
	v_pk_fma_f32 v[40:41], v[40:41], v[242:243], v[52:53] op_sel_hi:[1,0,1]
	v_pk_fma_f32 v[42:43], v[42:43], v[242:243], v[54:55] op_sel_hi:[1,0,1]
	v_pk_fma_f32 v[124:125], v[124:125], v[242:243], v[116:117] op_sel_hi:[1,0,1]
	v_pk_fma_f32 v[126:127], v[126:127], v[242:243], v[118:119] op_sel_hi:[1,0,1]
	v_pk_fma_f32 v[32:33], v[32:33], v[242:243], v[48:49] op_sel_hi:[1,0,1]
	v_pk_fma_f32 v[34:35], v[34:35], v[242:243], v[50:51] op_sel_hi:[1,0,1]
	v_pk_fma_f32 v[100:101], v[100:101], v[248:249], v[120:121] op_sel_hi:[1,0,1]
	v_pk_fma_f32 v[102:103], v[102:103], v[248:249], v[122:123] op_sel_hi:[1,0,1]
	v_pk_fma_f32 v[28:29], v[28:29], v[248:249], v[52:53] op_sel_hi:[1,0,1]
	v_pk_fma_f32 v[30:31], v[30:31], v[248:249], v[54:55] op_sel_hi:[1,0,1]
	v_pk_fma_f32 v[92:93], v[92:93], v[248:249], v[116:117] op_sel_hi:[1,0,1]
	v_pk_fma_f32 v[94:95], v[94:95], v[248:249], v[118:119] op_sel_hi:[1,0,1]
	v_pk_fma_f32 v[20:21], v[20:21], v[248:249], v[48:49] op_sel_hi:[1,0,1]
	v_pk_fma_f32 v[22:23], v[22:23], v[248:249], v[50:51] op_sel_hi:[1,0,1]
	v_pk_fma_f32 v[96:97], v[96:97], v[240:241], v[120:121] op_sel_hi:[1,0,1]
	v_pk_fma_f32 v[98:99], v[98:99], v[240:241], v[122:123] op_sel_hi:[1,0,1]
	v_pk_fma_f32 v[24:25], v[24:25], v[240:241], v[52:53] op_sel_hi:[1,0,1]
	v_pk_fma_f32 v[26:27], v[26:27], v[240:241], v[54:55] op_sel_hi:[1,0,1]
	v_pk_fma_f32 v[88:89], v[88:89], v[240:241], v[116:117] op_sel_hi:[1,0,1]
	v_pk_fma_f32 v[90:91], v[90:91], v[240:241], v[118:119] op_sel_hi:[1,0,1]
	v_pk_fma_f32 v[16:17], v[16:17], v[240:241], v[48:49] op_sel_hi:[1,0,1]
	v_pk_fma_f32 v[18:19], v[18:19], v[240:241], v[50:51] op_sel_hi:[1,0,1]
	v_pk_fma_f32 v[84:85], v[84:85], v[198:199], v[120:121] op_sel_hi:[1,0,1]
	v_pk_fma_f32 v[86:87], v[86:87], v[198:199], v[122:123] op_sel_hi:[1,0,1]
	v_pk_fma_f32 v[12:13], v[12:13], v[198:199], v[52:53] op_sel_hi:[1,0,1]
	v_pk_fma_f32 v[14:15], v[14:15], v[198:199], v[54:55] op_sel_hi:[1,0,1]
	v_pk_fma_f32 v[80:81], v[80:81], v[198:199], v[116:117] op_sel_hi:[1,0,1]
	v_pk_fma_f32 v[82:83], v[82:83], v[198:199], v[118:119] op_sel_hi:[1,0,1]
	v_pk_fma_f32 v[4:5], v[4:5], v[198:199], v[48:49] op_sel_hi:[1,0,1]
	v_pk_fma_f32 v[6:7], v[6:7], v[198:199], v[50:51] op_sel_hi:[1,0,1]
	v_pk_fma_f32 v[76:77], v[76:77], v[250:251], v[120:121] op_sel_hi:[1,0,1]
	v_pk_fma_f32 v[78:79], v[78:79], v[250:251], v[122:123] op_sel_hi:[1,0,1]
	v_pk_fma_f32 v[8:9], v[8:9], v[250:251], v[52:53] op_sel_hi:[1,0,1]
	v_pk_fma_f32 v[10:11], v[10:11], v[250:251], v[54:55] op_sel_hi:[1,0,1]
	v_pk_fma_f32 v[72:73], v[72:73], v[250:251], v[116:117] op_sel_hi:[1,0,1]
	v_pk_fma_f32 v[74:75], v[74:75], v[250:251], v[118:119] op_sel_hi:[1,0,1]
	v_pk_fma_f32 v[0:1], v[0:1], v[250:251], v[48:49] op_sel_hi:[1,0,1]
	v_pk_fma_f32 v[2:3], v[2:3], v[250:251], v[50:51] op_sel_hi:[1,0,1]
	v_mov_b64_e32 v[246:247], s[16:17]
	v_mad_i64_i32 v[246:247], vcc, v192, s90, v[246:247]
	v_lshl_add_u64 v[246:247], v[190:191], 1, v[246:247]
	v_ashrrev_i32_e32 v194, 4, v192
	v_and_b32_e32 v194, -4, v194
	v_add_u32_e32 v194, v194, v239
	v_mov_b64_e32 v[248:249], s[18:19]
	v_mad_i64_i32 v[248:249], vcc, v194, s91, v[248:249]
	v_lshl_add_u64 v[248:249], v[190:191], 1, v[248:249]
	v_mov_b32_e32 v244, v246
	v_mov_b32_e32 v245, v247
	v_mov_b32_e32 v250, v248
	v_mov_b32_e32 v251, v249
	v_add_co_u32_e32 v194, vcc, 0x1000, v250
	s_nop 1
	v_addc_co_u32_e32 v195, vcc, 0, v251, vcc
	v_mul_f32_e32 v116, v164, v152
	v_mul_f32_e32 v117, v165, v153
	v_mul_f32_e32 v118, v166, v154
	v_mul_f32_e32 v119, v167, v155
	v_mul_f32_e32 v120, v112, v144
	v_mul_f32_e32 v121, v113, v145
	v_mul_f32_e32 v122, v114, v146
	v_mul_f32_e32 v123, v115, v147
	v_fmac_f32_dpp v116, v152, v156 row_shr:1 row_mask:0xf bank_mask:0xf bound_ctrl:1
	v_fmac_f32_dpp v117, v153, v157 row_shr:1 row_mask:0xf bank_mask:0xf bound_ctrl:1
	v_fmac_f32_dpp v118, v154, v158 row_shr:1 row_mask:0xf bank_mask:0xf bound_ctrl:1
	v_fmac_f32_dpp v119, v155, v159 row_shr:1 row_mask:0xf bank_mask:0xf bound_ctrl:1
	v_fmac_f32_dpp v120, v144, v104 row_shr:1 row_mask:0xf bank_mask:0xf bound_ctrl:1
	v_fmac_f32_dpp v121, v145, v105 row_shr:1 row_mask:0xf bank_mask:0xf bound_ctrl:1
	v_fmac_f32_dpp v122, v146, v106 row_shr:1 row_mask:0xf bank_mask:0xf bound_ctrl:1
	v_fmac_f32_dpp v123, v147, v107 row_shr:1 row_mask:0xf bank_mask:0xf bound_ctrl:1
	v_fmac_f32_dpp v116, v152, v160 row_shl:1 row_mask:0xf bank_mask:0xf bound_ctrl:1
	v_fmac_f32_dpp v117, v153, v161 row_shl:1 row_mask:0xf bank_mask:0xf bound_ctrl:1
	v_fmac_f32_dpp v118, v154, v162 row_shl:1 row_mask:0xf bank_mask:0xf bound_ctrl:1
	v_fmac_f32_dpp v119, v155, v163 row_shl:1 row_mask:0xf bank_mask:0xf bound_ctrl:1
	v_fmac_f32_dpp v120, v144, v108 row_shl:1 row_mask:0xf bank_mask:0xf bound_ctrl:1
	v_fmac_f32_dpp v121, v145, v109 row_shl:1 row_mask:0xf bank_mask:0xf bound_ctrl:1
	v_fmac_f32_dpp v122, v146, v110 row_shl:1 row_mask:0xf bank_mask:0xf bound_ctrl:1
	v_fmac_f32_dpp v123, v147, v111 row_shl:1 row_mask:0xf bank_mask:0xf bound_ctrl:1
	v_fmac_f32_dpp v116, v148, v160 row_shr:15 row_mask:0xf bank_mask:0xf bound_ctrl:1
	v_fmac_f32_dpp v117, v149, v161 row_shr:15 row_mask:0xf bank_mask:0xf bound_ctrl:1
	v_fmac_f32_dpp v118, v150, v162 row_shr:15 row_mask:0xf bank_mask:0xf bound_ctrl:1
	v_fmac_f32_dpp v119, v151, v163 row_shr:15 row_mask:0xf bank_mask:0xf bound_ctrl:1
	v_fmac_f32_dpp v120, v140, v108 row_shr:15 row_mask:0xf bank_mask:0xf bound_ctrl:1
	v_fmac_f32_dpp v121, v141, v109 row_shr:15 row_mask:0xf bank_mask:0xf bound_ctrl:1
	v_fmac_f32_dpp v122, v142, v110 row_shr:15 row_mask:0xf bank_mask:0xf bound_ctrl:1
	v_fmac_f32_dpp v123, v143, v111 row_shr:15 row_mask:0xf bank_mask:0xf bound_ctrl:1
	v_pk_mul_f32 v[48:49], v[116:117], s[0:1]
	v_pk_mul_f32 v[50:51], v[118:119], s[0:1]
	v_pk_mul_f32 v[52:53], v[116:117], v[120:121]
	v_pk_mul_f32 v[54:55], v[118:119], v[122:123]
	v_exp_f32_e32 v48, v48
	v_exp_f32_e32 v49, v49
	v_exp_f32_e32 v50, v50
	v_exp_f32_e32 v51, v51
	v_cvt_pk_bf16_f32 v196, v152, v153
	v_cvt_pk_bf16_f32 v197, v154, v155
	v_cvt_pk_bf16_f32 v198, v144, v145
	v_cvt_pk_bf16_f32 v199, v146, v147
	v_pk_add_f32 v[48:49], v[48:49], 1.0 op_sel_hi:[1,0]
	v_pk_add_f32 v[50:51], v[50:51], 1.0 op_sel_hi:[1,0]
	v_rcp_f32_e32 v48, v48
	v_rcp_f32_e32 v49, v49
	v_rcp_f32_e32 v50, v50
	v_rcp_f32_e32 v51, v51
	s_nop 0
	v_pk_mul_f32 v[52:53], v[52:53], v[48:49]
	v_pk_mul_f32 v[54:55], v[54:55], v[50:51]
	v_cvt_pk_bf16_f32 v170, v52, v53
	v_cvt_pk_bf16_f32 v171, v54, v55
	s_and_saveexec_b64 vcc, s[12:13]
	global_store_dwordx2 v[250:251], v[196:197], off
	global_store_dwordx2 v[194:195], v[198:199], off offset:1536
	s_mov_b64 exec, vcc
	v_lshl_add_u64 v[244:245], v[244:245], 0, s[2:3]
	v_mul_f32_e32 v116, v164, v148
	v_mul_f32_e32 v117, v165, v149
	v_mul_f32_e32 v118, v166, v150
	v_mul_f32_e32 v119, v167, v151
	v_mul_f32_e32 v120, v112, v140
	v_mul_f32_e32 v121, v113, v141
	v_mul_f32_e32 v122, v114, v142
	v_mul_f32_e32 v123, v115, v143
	v_fmac_f32_dpp v116, v148, v156 row_shr:1 row_mask:0xf bank_mask:0xf bound_ctrl:1
	v_fmac_f32_dpp v117, v149, v157 row_shr:1 row_mask:0xf bank_mask:0xf bound_ctrl:1
	v_fmac_f32_dpp v118, v150, v158 row_shr:1 row_mask:0xf bank_mask:0xf bound_ctrl:1
	v_fmac_f32_dpp v119, v151, v159 row_shr:1 row_mask:0xf bank_mask:0xf bound_ctrl:1
	v_fmac_f32_dpp v120, v140, v104 row_shr:1 row_mask:0xf bank_mask:0xf bound_ctrl:1
	v_fmac_f32_dpp v121, v141, v105 row_shr:1 row_mask:0xf bank_mask:0xf bound_ctrl:1
	v_fmac_f32_dpp v122, v142, v106 row_shr:1 row_mask:0xf bank_mask:0xf bound_ctrl:1
	v_fmac_f32_dpp v123, v143, v107 row_shr:1 row_mask:0xf bank_mask:0xf bound_ctrl:1
	v_fmac_f32_dpp v116, v148, v160 row_shl:1 row_mask:0xf bank_mask:0xf bound_ctrl:1
	v_fmac_f32_dpp v117, v149, v161 row_shl:1 row_mask:0xf bank_mask:0xf bound_ctrl:1
	v_fmac_f32_dpp v118, v150, v162 row_shl:1 row_mask:0xf bank_mask:0xf bound_ctrl:1
	v_fmac_f32_dpp v119, v151, v163 row_shl:1 row_mask:0xf bank_mask:0xf bound_ctrl:1
	v_fmac_f32_dpp v120, v140, v108 row_shl:1 row_mask:0xf bank_mask:0xf bound_ctrl:1
	v_fmac_f32_dpp v121, v141, v109 row_shl:1 row_mask:0xf bank_mask:0xf bound_ctrl:1
	v_fmac_f32_dpp v122, v142, v110 row_shl:1 row_mask:0xf bank_mask:0xf bound_ctrl:1
	v_fmac_f32_dpp v123, v143, v111 row_shl:1 row_mask:0xf bank_mask:0xf bound_ctrl:1
	v_fmac_f32_dpp v116, v152, v156 row_shl:15 row_mask:0xf bank_mask:0xf bound_ctrl:1
	v_fmac_f32_dpp v117, v153, v157 row_shl:15 row_mask:0xf bank_mask:0xf bound_ctrl:1
	v_fmac_f32_dpp v118, v154, v158 row_shl:15 row_mask:0xf bank_mask:0xf bound_ctrl:1
	v_fmac_f32_dpp v119, v155, v159 row_shl:15 row_mask:0xf bank_mask:0xf bound_ctrl:1
	v_fmac_f32_dpp v120, v144, v104 row_shl:15 row_mask:0xf bank_mask:0xf bound_ctrl:1
	v_fmac_f32_dpp v121, v145, v105 row_shl:15 row_mask:0xf bank_mask:0xf bound_ctrl:1
	v_fmac_f32_dpp v122, v146, v106 row_shl:15 row_mask:0xf bank_mask:0xf bound_ctrl:1
	v_fmac_f32_dpp v123, v147, v107 row_shl:15 row_mask:0xf bank_mask:0xf bound_ctrl:1
	v_fmac_f32_dpp v116, v136, v160 row_shr:15 row_mask:0xf bank_mask:0xf bound_ctrl:1
	v_fmac_f32_dpp v117, v137, v161 row_shr:15 row_mask:0xf bank_mask:0xf bound_ctrl:1
	v_fmac_f32_dpp v118, v138, v162 row_shr:15 row_mask:0xf bank_mask:0xf bound_ctrl:1
	v_fmac_f32_dpp v119, v139, v163 row_shr:15 row_mask:0xf bank_mask:0xf bound_ctrl:1
	v_fmac_f32_dpp v120, v132, v108 row_shr:15 row_mask:0xf bank_mask:0xf bound_ctrl:1
	v_fmac_f32_dpp v121, v133, v109 row_shr:15 row_mask:0xf bank_mask:0xf bound_ctrl:1
	v_fmac_f32_dpp v122, v134, v110 row_shr:15 row_mask:0xf bank_mask:0xf bound_ctrl:1
	v_fmac_f32_dpp v123, v135, v111 row_shr:15 row_mask:0xf bank_mask:0xf bound_ctrl:1
	v_pk_mul_f32 v[48:49], v[116:117], s[0:1]
	v_pk_mul_f32 v[50:51], v[118:119], s[0:1]
	v_pk_mul_f32 v[52:53], v[116:117], v[120:121]
	v_pk_mul_f32 v[54:55], v[118:119], v[122:123]
	v_exp_f32_e32 v48, v48
	v_exp_f32_e32 v49, v49
	v_exp_f32_e32 v50, v50
	v_exp_f32_e32 v51, v51
	s_nop 0
	v_pk_add_f32 v[48:49], v[48:49], 1.0 op_sel_hi:[1,0]
	v_pk_add_f32 v[50:51], v[50:51], 1.0 op_sel_hi:[1,0]
	v_rcp_f32_e32 v48, v48
	v_rcp_f32_e32 v49, v49
	v_rcp_f32_e32 v50, v50
	v_rcp_f32_e32 v51, v51
	s_nop 0
	v_pk_mul_f32 v[52:53], v[52:53], v[48:49]
	v_pk_mul_f32 v[54:55], v[54:55], v[50:51]
	v_cvt_pk_bf16_f32 v152, v52, v53
	v_cvt_pk_bf16_f32 v153, v54, v55
	v_lshl_add_u64 v[244:245], v[244:245], 0, s[2:3]
	v_mul_f32_e32 v116, v164, v136
	v_mul_f32_e32 v117, v165, v137
	v_mul_f32_e32 v118, v166, v138
	v_mul_f32_e32 v119, v167, v139
	v_mul_f32_e32 v120, v112, v132
	v_mul_f32_e32 v121, v113, v133
	v_mul_f32_e32 v122, v114, v134
	v_mul_f32_e32 v123, v115, v135
	v_fmac_f32_dpp v116, v136, v156 row_shr:1 row_mask:0xf bank_mask:0xf bound_ctrl:1
	v_fmac_f32_dpp v117, v137, v157 row_shr:1 row_mask:0xf bank_mask:0xf bound_ctrl:1
	v_fmac_f32_dpp v118, v138, v158 row_shr:1 row_mask:0xf bank_mask:0xf bound_ctrl:1
	v_fmac_f32_dpp v119, v139, v159 row_shr:1 row_mask:0xf bank_mask:0xf bound_ctrl:1
	v_fmac_f32_dpp v120, v132, v104 row_shr:1 row_mask:0xf bank_mask:0xf bound_ctrl:1
	v_fmac_f32_dpp v121, v133, v105 row_shr:1 row_mask:0xf bank_mask:0xf bound_ctrl:1
	v_fmac_f32_dpp v122, v134, v106 row_shr:1 row_mask:0xf bank_mask:0xf bound_ctrl:1
	v_fmac_f32_dpp v123, v135, v107 row_shr:1 row_mask:0xf bank_mask:0xf bound_ctrl:1
	v_fmac_f32_dpp v116, v136, v160 row_shl:1 row_mask:0xf bank_mask:0xf bound_ctrl:1
	v_fmac_f32_dpp v117, v137, v161 row_shl:1 row_mask:0xf bank_mask:0xf bound_ctrl:1
	v_fmac_f32_dpp v118, v138, v162 row_shl:1 row_mask:0xf bank_mask:0xf bound_ctrl:1
	v_fmac_f32_dpp v119, v139, v163 row_shl:1 row_mask:0xf bank_mask:0xf bound_ctrl:1
	v_fmac_f32_dpp v120, v132, v108 row_shl:1 row_mask:0xf bank_mask:0xf bound_ctrl:1
	v_fmac_f32_dpp v121, v133, v109 row_shl:1 row_mask:0xf bank_mask:0xf bound_ctrl:1
	v_fmac_f32_dpp v122, v134, v110 row_shl:1 row_mask:0xf bank_mask:0xf bound_ctrl:1
	v_fmac_f32_dpp v123, v135, v111 row_shl:1 row_mask:0xf bank_mask:0xf bound_ctrl:1
	v_fmac_f32_dpp v116, v148, v156 row_shl:15 row_mask:0xf bank_mask:0xf bound_ctrl:1
	v_fmac_f32_dpp v117, v149, v157 row_shl:15 row_mask:0xf bank_mask:0xf bound_ctrl:1
	v_fmac_f32_dpp v118, v150, v158 row_shl:15 row_mask:0xf bank_mask:0xf bound_ctrl:1
	v_fmac_f32_dpp v119, v151, v159 row_shl:15 row_mask:0xf bank_mask:0xf bound_ctrl:1
	v_fmac_f32_dpp v120, v140, v104 row_shl:15 row_mask:0xf bank_mask:0xf bound_ctrl:1
	v_fmac_f32_dpp v121, v141, v105 row_shl:15 row_mask:0xf bank_mask:0xf bound_ctrl:1
	v_fmac_f32_dpp v122, v142, v106 row_shl:15 row_mask:0xf bank_mask:0xf bound_ctrl:1
	v_fmac_f32_dpp v123, v143, v107 row_shl:15 row_mask:0xf bank_mask:0xf bound_ctrl:1
	v_fmac_f32_dpp v116, v128, v160 row_shr:15 row_mask:0xf bank_mask:0xf bound_ctrl:1
	v_fmac_f32_dpp v117, v129, v161 row_shr:15 row_mask:0xf bank_mask:0xf bound_ctrl:1
	v_fmac_f32_dpp v118, v130, v162 row_shr:15 row_mask:0xf bank_mask:0xf bound_ctrl:1
	v_fmac_f32_dpp v119, v131, v163 row_shr:15 row_mask:0xf bank_mask:0xf bound_ctrl:1
	v_fmac_f32_dpp v120, v124, v108 row_shr:15 row_mask:0xf bank_mask:0xf bound_ctrl:1
	v_fmac_f32_dpp v121, v125, v109 row_shr:15 row_mask:0xf bank_mask:0xf bound_ctrl:1
	v_fmac_f32_dpp v122, v126, v110 row_shr:15 row_mask:0xf bank_mask:0xf bound_ctrl:1
	v_fmac_f32_dpp v123, v127, v111 row_shr:15 row_mask:0xf bank_mask:0xf bound_ctrl:1
	v_pk_mul_f32 v[48:49], v[116:117], s[0:1]
	v_pk_mul_f32 v[50:51], v[118:119], s[0:1]
	v_pk_mul_f32 v[52:53], v[116:117], v[120:121]
	v_pk_mul_f32 v[54:55], v[118:119], v[122:123]
	v_exp_f32_e32 v48, v48
	v_exp_f32_e32 v49, v49
	v_exp_f32_e32 v50, v50
	v_exp_f32_e32 v51, v51
	s_nop 0
	v_pk_add_f32 v[48:49], v[48:49], 1.0 op_sel_hi:[1,0]
	v_pk_add_f32 v[50:51], v[50:51], 1.0 op_sel_hi:[1,0]
	v_rcp_f32_e32 v48, v48
	v_rcp_f32_e32 v49, v49
	v_rcp_f32_e32 v50, v50
	v_rcp_f32_e32 v51, v51
	s_nop 0
	v_pk_mul_f32 v[52:53], v[52:53], v[48:49]
	v_pk_mul_f32 v[54:55], v[54:55], v[50:51]
	v_cvt_pk_bf16_f32 v148, v52, v53
	v_cvt_pk_bf16_f32 v149, v54, v55
	v_lshl_add_u64 v[244:245], v[244:245], 0, s[2:3]
	v_mul_f32_e32 v116, v164, v128
	v_mul_f32_e32 v117, v165, v129
	v_mul_f32_e32 v118, v166, v130
	v_mul_f32_e32 v119, v167, v131
	v_mul_f32_e32 v120, v112, v124
	v_mul_f32_e32 v121, v113, v125
	v_mul_f32_e32 v122, v114, v126
	v_mul_f32_e32 v123, v115, v127
	v_fmac_f32_dpp v116, v128, v156 row_shr:1 row_mask:0xf bank_mask:0xf bound_ctrl:1
	v_fmac_f32_dpp v117, v129, v157 row_shr:1 row_mask:0xf bank_mask:0xf bound_ctrl:1
	v_fmac_f32_dpp v118, v130, v158 row_shr:1 row_mask:0xf bank_mask:0xf bound_ctrl:1
	v_fmac_f32_dpp v119, v131, v159 row_shr:1 row_mask:0xf bank_mask:0xf bound_ctrl:1
	v_fmac_f32_dpp v120, v124, v104 row_shr:1 row_mask:0xf bank_mask:0xf bound_ctrl:1
	v_fmac_f32_dpp v121, v125, v105 row_shr:1 row_mask:0xf bank_mask:0xf bound_ctrl:1
	v_fmac_f32_dpp v122, v126, v106 row_shr:1 row_mask:0xf bank_mask:0xf bound_ctrl:1
	v_fmac_f32_dpp v123, v127, v107 row_shr:1 row_mask:0xf bank_mask:0xf bound_ctrl:1
	v_fmac_f32_dpp v116, v128, v160 row_shl:1 row_mask:0xf bank_mask:0xf bound_ctrl:1
	v_fmac_f32_dpp v117, v129, v161 row_shl:1 row_mask:0xf bank_mask:0xf bound_ctrl:1
	v_fmac_f32_dpp v118, v130, v162 row_shl:1 row_mask:0xf bank_mask:0xf bound_ctrl:1
	v_fmac_f32_dpp v119, v131, v163 row_shl:1 row_mask:0xf bank_mask:0xf bound_ctrl:1
	v_fmac_f32_dpp v120, v124, v108 row_shl:1 row_mask:0xf bank_mask:0xf bound_ctrl:1
	v_fmac_f32_dpp v121, v125, v109 row_shl:1 row_mask:0xf bank_mask:0xf bound_ctrl:1
	v_fmac_f32_dpp v122, v126, v110 row_shl:1 row_mask:0xf bank_mask:0xf bound_ctrl:1
	v_fmac_f32_dpp v123, v127, v111 row_shl:1 row_mask:0xf bank_mask:0xf bound_ctrl:1
	v_fmac_f32_dpp v116, v136, v156 row_shl:15 row_mask:0xf bank_mask:0xf bound_ctrl:1
	v_fmac_f32_dpp v117, v137, v157 row_shl:15 row_mask:0xf bank_mask:0xf bound_ctrl:1
	v_fmac_f32_dpp v118, v138, v158 row_shl:15 row_mask:0xf bank_mask:0xf bound_ctrl:1
	v_fmac_f32_dpp v119, v139, v159 row_shl:15 row_mask:0xf bank_mask:0xf bound_ctrl:1
	v_fmac_f32_dpp v120, v132, v104 row_shl:15 row_mask:0xf bank_mask:0xf bound_ctrl:1
	v_fmac_f32_dpp v121, v133, v105 row_shl:15 row_mask:0xf bank_mask:0xf bound_ctrl:1
	v_fmac_f32_dpp v122, v134, v106 row_shl:15 row_mask:0xf bank_mask:0xf bound_ctrl:1
	v_fmac_f32_dpp v123, v135, v107 row_shl:15 row_mask:0xf bank_mask:0xf bound_ctrl:1
	v_pk_mul_f32 v[48:49], v[116:117], s[0:1]
	v_pk_mul_f32 v[50:51], v[118:119], s[0:1]
	v_pk_mul_f32 v[52:53], v[116:117], v[120:121]
	v_pk_mul_f32 v[54:55], v[118:119], v[122:123]
	v_exp_f32_e32 v48, v48
	v_exp_f32_e32 v49, v49
	v_exp_f32_e32 v50, v50
	v_exp_f32_e32 v51, v51
	v_cvt_pk_bf16_f32 v196, v128, v129
	v_cvt_pk_bf16_f32 v197, v130, v131
	v_cvt_pk_bf16_f32 v198, v124, v125
	v_cvt_pk_bf16_f32 v199, v126, v127
	v_pk_add_f32 v[48:49], v[48:49], 1.0 op_sel_hi:[1,0]
	v_pk_add_f32 v[50:51], v[50:51], 1.0 op_sel_hi:[1,0]
	v_rcp_f32_e32 v48, v48
	v_rcp_f32_e32 v49, v49
	v_rcp_f32_e32 v50, v50
	v_rcp_f32_e32 v51, v51
	s_nop 0
	v_pk_mul_f32 v[52:53], v[52:53], v[48:49]
	v_pk_mul_f32 v[54:55], v[54:55], v[50:51]
	v_cvt_pk_bf16_f32 v136, v52, v53
	v_cvt_pk_bf16_f32 v137, v54, v55
	v_mov_b64 v[128:129], v[170:171]
	v_add_co_u32_e32 v250, vcc, 0xfffdf000, v250
	s_nop 1
	v_addc_co_u32_e32 v251, vcc, -1, v251, vcc
	v_add_co_u32_e32 v194, vcc, 0x1000, v250
	s_nop 1
	v_addc_co_u32_e32 v195, vcc, 0, v251, vcc
	s_and_saveexec_b64 vcc, s[14:15]
	global_store_dwordx2 v[250:251], v[196:197], off
	global_store_dwordx2 v[194:195], v[198:199], off offset:1536
	s_mov_b64 exec, vcc
	s_cmp_lg_u32 s83, 0
	s_cbranch_scc1 .Lup_n1
	v_add_co_u32_e32 v244, vcc, 0xb0000, v246
	s_nop 1
	v_addc_co_u32_e32 v245, vcc, 0, v247, vcc
	v_add_co_u32_e32 v250, vcc, 0x16000, v248
	s_nop 1
	v_addc_co_u32_e32 v251, vcc, 0, v249, vcc
	v_add_co_u32_e32 v194, vcc, 0x1000, v250
	s_nop 1
	v_addc_co_u32_e32 v195, vcc, 0, v251, vcc
	v_mul_f32_e32 v116, v164, v100
	v_mul_f32_e32 v117, v165, v101
	v_mul_f32_e32 v118, v166, v102
	v_mul_f32_e32 v119, v167, v103
	v_mul_f32_e32 v120, v112, v92
	v_mul_f32_e32 v121, v113, v93
	v_mul_f32_e32 v122, v114, v94
	v_mul_f32_e32 v123, v115, v95
	v_fmac_f32_dpp v116, v100, v156 row_shr:1 row_mask:0xf bank_mask:0xf bound_ctrl:1
	v_fmac_f32_dpp v117, v101, v157 row_shr:1 row_mask:0xf bank_mask:0xf bound_ctrl:1
	v_fmac_f32_dpp v118, v102, v158 row_shr:1 row_mask:0xf bank_mask:0xf bound_ctrl:1
	v_fmac_f32_dpp v119, v103, v159 row_shr:1 row_mask:0xf bank_mask:0xf bound_ctrl:1
	v_fmac_f32_dpp v120, v92, v104 row_shr:1 row_mask:0xf bank_mask:0xf bound_ctrl:1
	v_fmac_f32_dpp v121, v93, v105 row_shr:1 row_mask:0xf bank_mask:0xf bound_ctrl:1
	v_fmac_f32_dpp v122, v94, v106 row_shr:1 row_mask:0xf bank_mask:0xf bound_ctrl:1
	v_fmac_f32_dpp v123, v95, v107 row_shr:1 row_mask:0xf bank_mask:0xf bound_ctrl:1
	v_fmac_f32_dpp v116, v100, v160 row_shl:1 row_mask:0xf bank_mask:0xf bound_ctrl:1
	v_fmac_f32_dpp v117, v101, v161 row_shl:1 row_mask:0xf bank_mask:0xf bound_ctrl:1
	v_fmac_f32_dpp v118, v102, v162 row_shl:1 row_mask:0xf bank_mask:0xf bound_ctrl:1
	v_fmac_f32_dpp v119, v103, v163 row_shl:1 row_mask:0xf bank_mask:0xf bound_ctrl:1
	v_fmac_f32_dpp v120, v92, v108 row_shl:1 row_mask:0xf bank_mask:0xf bound_ctrl:1
	v_fmac_f32_dpp v121, v93, v109 row_shl:1 row_mask:0xf bank_mask:0xf bound_ctrl:1
	v_fmac_f32_dpp v122, v94, v110 row_shl:1 row_mask:0xf bank_mask:0xf bound_ctrl:1
	v_fmac_f32_dpp v123, v95, v111 row_shl:1 row_mask:0xf bank_mask:0xf bound_ctrl:1
	v_fmac_f32_dpp v116, v96, v160 row_shr:15 row_mask:0xf bank_mask:0xf bound_ctrl:1
	v_fmac_f32_dpp v117, v97, v161 row_shr:15 row_mask:0xf bank_mask:0xf bound_ctrl:1
	v_fmac_f32_dpp v118, v98, v162 row_shr:15 row_mask:0xf bank_mask:0xf bound_ctrl:1
	v_fmac_f32_dpp v119, v99, v163 row_shr:15 row_mask:0xf bank_mask:0xf bound_ctrl:1
	v_fmac_f32_dpp v120, v88, v108 row_shr:15 row_mask:0xf bank_mask:0xf bound_ctrl:1
	v_fmac_f32_dpp v121, v89, v109 row_shr:15 row_mask:0xf bank_mask:0xf bound_ctrl:1
	v_fmac_f32_dpp v122, v90, v110 row_shr:15 row_mask:0xf bank_mask:0xf bound_ctrl:1
	v_fmac_f32_dpp v123, v91, v111 row_shr:15 row_mask:0xf bank_mask:0xf bound_ctrl:1
	v_pk_mul_f32 v[48:49], v[116:117], s[0:1]
	v_pk_mul_f32 v[50:51], v[118:119], s[0:1]
	v_pk_mul_f32 v[52:53], v[116:117], v[120:121]
	v_pk_mul_f32 v[54:55], v[118:119], v[122:123]
	v_exp_f32_e32 v48, v48
	v_exp_f32_e32 v49, v49
	v_exp_f32_e32 v50, v50
	v_exp_f32_e32 v51, v51
	v_cvt_pk_bf16_f32 v196, v100, v101
	v_cvt_pk_bf16_f32 v197, v102, v103
	v_cvt_pk_bf16_f32 v198, v92, v93
	v_cvt_pk_bf16_f32 v199, v94, v95
	v_pk_add_f32 v[48:49], v[48:49], 1.0 op_sel_hi:[1,0]
	v_pk_add_f32 v[50:51], v[50:51], 1.0 op_sel_hi:[1,0]
	v_rcp_f32_e32 v48, v48
	v_rcp_f32_e32 v49, v49
	v_rcp_f32_e32 v50, v50
	v_rcp_f32_e32 v51, v51
	s_nop 0
	v_pk_mul_f32 v[52:53], v[52:53], v[48:49]
	v_pk_mul_f32 v[54:55], v[54:55], v[50:51]
	v_cvt_pk_bf16_f32 v170, v52, v53
	v_cvt_pk_bf16_f32 v171, v54, v55
	s_and_saveexec_b64 vcc, s[12:13]
	global_store_dwordx2 v[250:251], v[196:197], off
	global_store_dwordx2 v[194:195], v[198:199], off offset:1536
	s_mov_b64 exec, vcc
	v_lshl_add_u64 v[244:245], v[244:245], 0, s[2:3]
	v_mul_f32_e32 v116, v164, v96
	v_mul_f32_e32 v117, v165, v97
	v_mul_f32_e32 v118, v166, v98
	v_mul_f32_e32 v119, v167, v99
	v_mul_f32_e32 v120, v112, v88
	v_mul_f32_e32 v121, v113, v89
	v_mul_f32_e32 v122, v114, v90
	v_mul_f32_e32 v123, v115, v91
	v_fmac_f32_dpp v116, v96, v156 row_shr:1 row_mask:0xf bank_mask:0xf bound_ctrl:1
	v_fmac_f32_dpp v117, v97, v157 row_shr:1 row_mask:0xf bank_mask:0xf bound_ctrl:1
	v_fmac_f32_dpp v118, v98, v158 row_shr:1 row_mask:0xf bank_mask:0xf bound_ctrl:1
	v_fmac_f32_dpp v119, v99, v159 row_shr:1 row_mask:0xf bank_mask:0xf bound_ctrl:1
	v_fmac_f32_dpp v120, v88, v104 row_shr:1 row_mask:0xf bank_mask:0xf bound_ctrl:1
	v_fmac_f32_dpp v121, v89, v105 row_shr:1 row_mask:0xf bank_mask:0xf bound_ctrl:1
	v_fmac_f32_dpp v122, v90, v106 row_shr:1 row_mask:0xf bank_mask:0xf bound_ctrl:1
	v_fmac_f32_dpp v123, v91, v107 row_shr:1 row_mask:0xf bank_mask:0xf bound_ctrl:1
	v_fmac_f32_dpp v116, v96, v160 row_shl:1 row_mask:0xf bank_mask:0xf bound_ctrl:1
	v_fmac_f32_dpp v117, v97, v161 row_shl:1 row_mask:0xf bank_mask:0xf bound_ctrl:1
	v_fmac_f32_dpp v118, v98, v162 row_shl:1 row_mask:0xf bank_mask:0xf bound_ctrl:1
	v_fmac_f32_dpp v119, v99, v163 row_shl:1 row_mask:0xf bank_mask:0xf bound_ctrl:1
	v_fmac_f32_dpp v120, v88, v108 row_shl:1 row_mask:0xf bank_mask:0xf bound_ctrl:1
	v_fmac_f32_dpp v121, v89, v109 row_shl:1 row_mask:0xf bank_mask:0xf bound_ctrl:1
	v_fmac_f32_dpp v122, v90, v110 row_shl:1 row_mask:0xf bank_mask:0xf bound_ctrl:1
	v_fmac_f32_dpp v123, v91, v111 row_shl:1 row_mask:0xf bank_mask:0xf bound_ctrl:1
	v_fmac_f32_dpp v116, v100, v156 row_shl:15 row_mask:0xf bank_mask:0xf bound_ctrl:1
	v_fmac_f32_dpp v117, v101, v157 row_shl:15 row_mask:0xf bank_mask:0xf bound_ctrl:1
	v_fmac_f32_dpp v118, v102, v158 row_shl:15 row_mask:0xf bank_mask:0xf bound_ctrl:1
	v_fmac_f32_dpp v119, v103, v159 row_shl:15 row_mask:0xf bank_mask:0xf bound_ctrl:1
	v_fmac_f32_dpp v120, v92, v104 row_shl:15 row_mask:0xf bank_mask:0xf bound_ctrl:1
	v_fmac_f32_dpp v121, v93, v105 row_shl:15 row_mask:0xf bank_mask:0xf bound_ctrl:1
	v_fmac_f32_dpp v122, v94, v106 row_shl:15 row_mask:0xf bank_mask:0xf bound_ctrl:1
	v_fmac_f32_dpp v123, v95, v107 row_shl:15 row_mask:0xf bank_mask:0xf bound_ctrl:1
	v_fmac_f32_dpp v116, v84, v160 row_shr:15 row_mask:0xf bank_mask:0xf bound_ctrl:1
	v_fmac_f32_dpp v117, v85, v161 row_shr:15 row_mask:0xf bank_mask:0xf bound_ctrl:1
	v_fmac_f32_dpp v118, v86, v162 row_shr:15 row_mask:0xf bank_mask:0xf bound_ctrl:1
	v_fmac_f32_dpp v119, v87, v163 row_shr:15 row_mask:0xf bank_mask:0xf bound_ctrl:1
	v_fmac_f32_dpp v120, v80, v108 row_shr:15 row_mask:0xf bank_mask:0xf bound_ctrl:1
	v_fmac_f32_dpp v121, v81, v109 row_shr:15 row_mask:0xf bank_mask:0xf bound_ctrl:1
	v_fmac_f32_dpp v122, v82, v110 row_shr:15 row_mask:0xf bank_mask:0xf bound_ctrl:1
	v_fmac_f32_dpp v123, v83, v111 row_shr:15 row_mask:0xf bank_mask:0xf bound_ctrl:1
	v_pk_mul_f32 v[48:49], v[116:117], s[0:1]
	v_pk_mul_f32 v[50:51], v[118:119], s[0:1]
	v_pk_mul_f32 v[52:53], v[116:117], v[120:121]
	v_pk_mul_f32 v[54:55], v[118:119], v[122:123]
	v_exp_f32_e32 v48, v48
	v_exp_f32_e32 v49, v49
	v_exp_f32_e32 v50, v50
	v_exp_f32_e32 v51, v51
	s_nop 0
	v_pk_add_f32 v[48:49], v[48:49], 1.0 op_sel_hi:[1,0]
	v_pk_add_f32 v[50:51], v[50:51], 1.0 op_sel_hi:[1,0]
	v_rcp_f32_e32 v48, v48
	v_rcp_f32_e32 v49, v49
	v_rcp_f32_e32 v50, v50
	v_rcp_f32_e32 v51, v51
	s_nop 0
	v_pk_mul_f32 v[52:53], v[52:53], v[48:49]
	v_pk_mul_f32 v[54:55], v[54:55], v[50:51]
	v_cvt_pk_bf16_f32 v100, v52, v53
	v_cvt_pk_bf16_f32 v101, v54, v55
	v_lshl_add_u64 v[244:245], v[244:245], 0, s[2:3]
	v_mul_f32_e32 v116, v164, v84
	v_mul_f32_e32 v117, v165, v85
	v_mul_f32_e32 v118, v166, v86
	v_mul_f32_e32 v119, v167, v87
	v_mul_f32_e32 v120, v112, v80
	v_mul_f32_e32 v121, v113, v81
	v_mul_f32_e32 v122, v114, v82
	v_mul_f32_e32 v123, v115, v83
	v_fmac_f32_dpp v116, v84, v156 row_shr:1 row_mask:0xf bank_mask:0xf bound_ctrl:1
	v_fmac_f32_dpp v117, v85, v157 row_shr:1 row_mask:0xf bank_mask:0xf bound_ctrl:1
	v_fmac_f32_dpp v118, v86, v158 row_shr:1 row_mask:0xf bank_mask:0xf bound_ctrl:1
	v_fmac_f32_dpp v119, v87, v159 row_shr:1 row_mask:0xf bank_mask:0xf bound_ctrl:1
	v_fmac_f32_dpp v120, v80, v104 row_shr:1 row_mask:0xf bank_mask:0xf bound_ctrl:1
	v_fmac_f32_dpp v121, v81, v105 row_shr:1 row_mask:0xf bank_mask:0xf bound_ctrl:1
	v_fmac_f32_dpp v122, v82, v106 row_shr:1 row_mask:0xf bank_mask:0xf bound_ctrl:1
	v_fmac_f32_dpp v123, v83, v107 row_shr:1 row_mask:0xf bank_mask:0xf bound_ctrl:1
	v_fmac_f32_dpp v116, v84, v160 row_shl:1 row_mask:0xf bank_mask:0xf bound_ctrl:1
	v_fmac_f32_dpp v117, v85, v161 row_shl:1 row_mask:0xf bank_mask:0xf bound_ctrl:1
	v_fmac_f32_dpp v118, v86, v162 row_shl:1 row_mask:0xf bank_mask:0xf bound_ctrl:1
	v_fmac_f32_dpp v119, v87, v163 row_shl:1 row_mask:0xf bank_mask:0xf bound_ctrl:1
	v_fmac_f32_dpp v120, v80, v108 row_shl:1 row_mask:0xf bank_mask:0xf bound_ctrl:1
	v_fmac_f32_dpp v121, v81, v109 row_shl:1 row_mask:0xf bank_mask:0xf bound_ctrl:1
	v_fmac_f32_dpp v122, v82, v110 row_shl:1 row_mask:0xf bank_mask:0xf bound_ctrl:1
	v_fmac_f32_dpp v123, v83, v111 row_shl:1 row_mask:0xf bank_mask:0xf bound_ctrl:1
	v_fmac_f32_dpp v116, v96, v156 row_shl:15 row_mask:0xf bank_mask:0xf bound_ctrl:1
	v_fmac_f32_dpp v117, v97, v157 row_shl:15 row_mask:0xf bank_mask:0xf bound_ctrl:1
	v_fmac_f32_dpp v118, v98, v158 row_shl:15 row_mask:0xf bank_mask:0xf bound_ctrl:1
	v_fmac_f32_dpp v119, v99, v159 row_shl:15 row_mask:0xf bank_mask:0xf bound_ctrl:1
	v_fmac_f32_dpp v120, v88, v104 row_shl:15 row_mask:0xf bank_mask:0xf bound_ctrl:1
	v_fmac_f32_dpp v121, v89, v105 row_shl:15 row_mask:0xf bank_mask:0xf bound_ctrl:1
	v_fmac_f32_dpp v122, v90, v106 row_shl:15 row_mask:0xf bank_mask:0xf bound_ctrl:1
	v_fmac_f32_dpp v123, v91, v107 row_shl:15 row_mask:0xf bank_mask:0xf bound_ctrl:1
	v_fmac_f32_dpp v116, v76, v160 row_shr:15 row_mask:0xf bank_mask:0xf bound_ctrl:1
	v_fmac_f32_dpp v117, v77, v161 row_shr:15 row_mask:0xf bank_mask:0xf bound_ctrl:1
	v_fmac_f32_dpp v118, v78, v162 row_shr:15 row_mask:0xf bank_mask:0xf bound_ctrl:1
	v_fmac_f32_dpp v119, v79, v163 row_shr:15 row_mask:0xf bank_mask:0xf bound_ctrl:1
	v_fmac_f32_dpp v120, v72, v108 row_shr:15 row_mask:0xf bank_mask:0xf bound_ctrl:1
	v_fmac_f32_dpp v121, v73, v109 row_shr:15 row_mask:0xf bank_mask:0xf bound_ctrl:1
	v_fmac_f32_dpp v122, v74, v110 row_shr:15 row_mask:0xf bank_mask:0xf bound_ctrl:1
	v_fmac_f32_dpp v123, v75, v111 row_shr:15 row_mask:0xf bank_mask:0xf bound_ctrl:1
	v_pk_mul_f32 v[48:49], v[116:117], s[0:1]
	v_pk_mul_f32 v[50:51], v[118:119], s[0:1]
	v_pk_mul_f32 v[52:53], v[116:117], v[120:121]
	v_pk_mul_f32 v[54:55], v[118:119], v[122:123]
	v_exp_f32_e32 v48, v48
	v_exp_f32_e32 v49, v49
	v_exp_f32_e32 v50, v50
	v_exp_f32_e32 v51, v51
	s_nop 0
	v_pk_add_f32 v[48:49], v[48:49], 1.0 op_sel_hi:[1,0]
	v_pk_add_f32 v[50:51], v[50:51], 1.0 op_sel_hi:[1,0]
	v_rcp_f32_e32 v48, v48
	v_rcp_f32_e32 v49, v49
	v_rcp_f32_e32 v50, v50
	v_rcp_f32_e32 v51, v51
	s_nop 0
	v_pk_mul_f32 v[52:53], v[52:53], v[48:49]
	v_pk_mul_f32 v[54:55], v[54:55], v[50:51]
	v_cvt_pk_bf16_f32 v96, v52, v53
	v_cvt_pk_bf16_f32 v97, v54, v55
	v_lshl_add_u64 v[244:245], v[244:245], 0, s[2:3]
	v_mul_f32_e32 v116, v164, v76
	v_mul_f32_e32 v117, v165, v77
	v_mul_f32_e32 v118, v166, v78
	v_mul_f32_e32 v119, v167, v79
	v_mul_f32_e32 v120, v112, v72
	v_mul_f32_e32 v121, v113, v73
	v_mul_f32_e32 v122, v114, v74
	v_mul_f32_e32 v123, v115, v75
	v_fmac_f32_dpp v116, v76, v156 row_shr:1 row_mask:0xf bank_mask:0xf bound_ctrl:1
	v_fmac_f32_dpp v117, v77, v157 row_shr:1 row_mask:0xf bank_mask:0xf bound_ctrl:1
	v_fmac_f32_dpp v118, v78, v158 row_shr:1 row_mask:0xf bank_mask:0xf bound_ctrl:1
	v_fmac_f32_dpp v119, v79, v159 row_shr:1 row_mask:0xf bank_mask:0xf bound_ctrl:1
	v_fmac_f32_dpp v120, v72, v104 row_shr:1 row_mask:0xf bank_mask:0xf bound_ctrl:1
	v_fmac_f32_dpp v121, v73, v105 row_shr:1 row_mask:0xf bank_mask:0xf bound_ctrl:1
	v_fmac_f32_dpp v122, v74, v106 row_shr:1 row_mask:0xf bank_mask:0xf bound_ctrl:1
	v_fmac_f32_dpp v123, v75, v107 row_shr:1 row_mask:0xf bank_mask:0xf bound_ctrl:1
	v_fmac_f32_dpp v116, v76, v160 row_shl:1 row_mask:0xf bank_mask:0xf bound_ctrl:1
	v_fmac_f32_dpp v117, v77, v161 row_shl:1 row_mask:0xf bank_mask:0xf bound_ctrl:1
	v_fmac_f32_dpp v118, v78, v162 row_shl:1 row_mask:0xf bank_mask:0xf bound_ctrl:1
	v_fmac_f32_dpp v119, v79, v163 row_shl:1 row_mask:0xf bank_mask:0xf bound_ctrl:1
	v_fmac_f32_dpp v120, v72, v108 row_shl:1 row_mask:0xf bank_mask:0xf bound_ctrl:1
	v_fmac_f32_dpp v121, v73, v109 row_shl:1 row_mask:0xf bank_mask:0xf bound_ctrl:1
	v_fmac_f32_dpp v122, v74, v110 row_shl:1 row_mask:0xf bank_mask:0xf bound_ctrl:1
	v_fmac_f32_dpp v123, v75, v111 row_shl:1 row_mask:0xf bank_mask:0xf bound_ctrl:1
	v_fmac_f32_dpp v116, v84, v156 row_shl:15 row_mask:0xf bank_mask:0xf bound_ctrl:1
	v_fmac_f32_dpp v117, v85, v157 row_shl:15 row_mask:0xf bank_mask:0xf bound_ctrl:1
	v_fmac_f32_dpp v118, v86, v158 row_shl:15 row_mask:0xf bank_mask:0xf bound_ctrl:1
	v_fmac_f32_dpp v119, v87, v159 row_shl:15 row_mask:0xf bank_mask:0xf bound_ctrl:1
	v_fmac_f32_dpp v120, v80, v104 row_shl:15 row_mask:0xf bank_mask:0xf bound_ctrl:1
	v_fmac_f32_dpp v121, v81, v105 row_shl:15 row_mask:0xf bank_mask:0xf bound_ctrl:1
	v_fmac_f32_dpp v122, v82, v106 row_shl:15 row_mask:0xf bank_mask:0xf bound_ctrl:1
	v_fmac_f32_dpp v123, v83, v107 row_shl:15 row_mask:0xf bank_mask:0xf bound_ctrl:1
	v_pk_mul_f32 v[48:49], v[116:117], s[0:1]
	v_pk_mul_f32 v[50:51], v[118:119], s[0:1]
	v_pk_mul_f32 v[52:53], v[116:117], v[120:121]
	v_pk_mul_f32 v[54:55], v[118:119], v[122:123]
	v_exp_f32_e32 v48, v48
	v_exp_f32_e32 v49, v49
	v_exp_f32_e32 v50, v50
	v_exp_f32_e32 v51, v51
	v_cvt_pk_bf16_f32 v196, v76, v77
	v_cvt_pk_bf16_f32 v197, v78, v79
	v_cvt_pk_bf16_f32 v198, v72, v73
	v_cvt_pk_bf16_f32 v199, v74, v75
	v_pk_add_f32 v[48:49], v[48:49], 1.0 op_sel_hi:[1,0]
	v_pk_add_f32 v[50:51], v[50:51], 1.0 op_sel_hi:[1,0]
	v_rcp_f32_e32 v48, v48
	v_rcp_f32_e32 v49, v49
	v_rcp_f32_e32 v50, v50
	v_rcp_f32_e32 v51, v51
	s_nop 0
	v_pk_mul_f32 v[52:53], v[52:53], v[48:49]
	v_pk_mul_f32 v[54:55], v[54:55], v[50:51]
	v_cvt_pk_bf16_f32 v84, v52, v53
	v_cvt_pk_bf16_f32 v85, v54, v55
	v_mov_b64 v[76:77], v[170:171]
	v_add_co_u32_e32 v250, vcc, 0xfffdf000, v250
	s_nop 1
	v_addc_co_u32_e32 v251, vcc, -1, v251, vcc
	v_add_co_u32_e32 v194, vcc, 0x1000, v250
	s_nop 1
	v_addc_co_u32_e32 v195, vcc, 0, v251, vcc
	s_and_saveexec_b64 vcc, s[14:15]
	global_store_dwordx2 v[250:251], v[196:197], off
	global_store_dwordx2 v[194:195], v[198:199], off offset:1536
	s_mov_b64 exec, vcc
.Lup_n1:
	v_mov_b32_e32 v244, v246
	v_mov_b32_e32 v245, v247
	v_mov_b32_e32 v250, v248
	v_mov_b32_e32 v251, v249
	v_add_co_u32_e32 v194, vcc, 0x1000, v250
	s_nop 1
	v_addc_co_u32_e32 v195, vcc, 0, v251, vcc
	v_mul_f32_e32 v116, v208, v68
	v_mul_f32_e32 v117, v209, v69
	v_mul_f32_e32 v118, v210, v70
	v_mul_f32_e32 v119, v211, v71
	v_mul_f32_e32 v120, v212, v60
	v_mul_f32_e32 v121, v213, v61
	v_mul_f32_e32 v122, v214, v62
	v_mul_f32_e32 v123, v215, v63
	v_fmac_f32_dpp v116, v68, v220 row_shr:1 row_mask:0xf bank_mask:0xf bound_ctrl:1
	v_fmac_f32_dpp v117, v69, v221 row_shr:1 row_mask:0xf bank_mask:0xf bound_ctrl:1
	v_fmac_f32_dpp v118, v70, v222 row_shr:1 row_mask:0xf bank_mask:0xf bound_ctrl:1
	v_fmac_f32_dpp v119, v71, v223 row_shr:1 row_mask:0xf bank_mask:0xf bound_ctrl:1
	v_fmac_f32_dpp v120, v60, v204 row_shr:1 row_mask:0xf bank_mask:0xf bound_ctrl:1
	v_fmac_f32_dpp v121, v61, v205 row_shr:1 row_mask:0xf bank_mask:0xf bound_ctrl:1
	v_fmac_f32_dpp v122, v62, v206 row_shr:1 row_mask:0xf bank_mask:0xf bound_ctrl:1
	v_fmac_f32_dpp v123, v63, v207 row_shr:1 row_mask:0xf bank_mask:0xf bound_ctrl:1
	v_fmac_f32_dpp v116, v68, v216 row_shl:1 row_mask:0xf bank_mask:0xf bound_ctrl:1
	v_fmac_f32_dpp v117, v69, v217 row_shl:1 row_mask:0xf bank_mask:0xf bound_ctrl:1
	v_fmac_f32_dpp v118, v70, v218 row_shl:1 row_mask:0xf bank_mask:0xf bound_ctrl:1
	v_fmac_f32_dpp v119, v71, v219 row_shl:1 row_mask:0xf bank_mask:0xf bound_ctrl:1
	v_fmac_f32_dpp v120, v60, v200 row_shl:1 row_mask:0xf bank_mask:0xf bound_ctrl:1
	v_fmac_f32_dpp v121, v61, v201 row_shl:1 row_mask:0xf bank_mask:0xf bound_ctrl:1
	v_fmac_f32_dpp v122, v62, v202 row_shl:1 row_mask:0xf bank_mask:0xf bound_ctrl:1
	v_fmac_f32_dpp v123, v63, v203 row_shl:1 row_mask:0xf bank_mask:0xf bound_ctrl:1
	v_fmac_f32_dpp v116, v64, v216 row_shr:15 row_mask:0xf bank_mask:0xf bound_ctrl:1
	v_fmac_f32_dpp v117, v65, v217 row_shr:15 row_mask:0xf bank_mask:0xf bound_ctrl:1
	v_fmac_f32_dpp v118, v66, v218 row_shr:15 row_mask:0xf bank_mask:0xf bound_ctrl:1
	v_fmac_f32_dpp v119, v67, v219 row_shr:15 row_mask:0xf bank_mask:0xf bound_ctrl:1
	v_fmac_f32_dpp v120, v56, v200 row_shr:15 row_mask:0xf bank_mask:0xf bound_ctrl:1
	v_fmac_f32_dpp v121, v57, v201 row_shr:15 row_mask:0xf bank_mask:0xf bound_ctrl:1
	v_fmac_f32_dpp v122, v58, v202 row_shr:15 row_mask:0xf bank_mask:0xf bound_ctrl:1
	v_fmac_f32_dpp v123, v59, v203 row_shr:15 row_mask:0xf bank_mask:0xf bound_ctrl:1
	v_pk_mul_f32 v[48:49], v[116:117], s[0:1]
	v_pk_mul_f32 v[50:51], v[118:119], s[0:1]
	v_pk_mul_f32 v[52:53], v[116:117], v[120:121]
	v_pk_mul_f32 v[54:55], v[118:119], v[122:123]
	v_exp_f32_e32 v48, v48
	v_exp_f32_e32 v49, v49
	v_exp_f32_e32 v50, v50
	v_exp_f32_e32 v51, v51
	v_cvt_pk_bf16_f32 v196, v68, v69
	v_cvt_pk_bf16_f32 v197, v70, v71
	v_cvt_pk_bf16_f32 v198, v60, v61
	v_cvt_pk_bf16_f32 v199, v62, v63
	v_pk_add_f32 v[48:49], v[48:49], 1.0 op_sel_hi:[1,0]
	v_pk_add_f32 v[50:51], v[50:51], 1.0 op_sel_hi:[1,0]
	v_rcp_f32_e32 v48, v48
	v_rcp_f32_e32 v49, v49
	v_rcp_f32_e32 v50, v50
	v_rcp_f32_e32 v51, v51
	s_nop 0
	v_pk_mul_f32 v[52:53], v[52:53], v[48:49]
	v_pk_mul_f32 v[54:55], v[54:55], v[50:51]
	v_cvt_pk_bf16_f32 v130, v52, v53
	v_cvt_pk_bf16_f32 v131, v54, v55
	s_and_saveexec_b64 vcc, s[10:11]
	global_store_dwordx4 v[244:245], v[128:131], off
	s_mov_b64 exec, vcc
	s_and_saveexec_b64 vcc, s[12:13]
	global_store_dwordx2 v[250:251], v[196:197], off offset:8
	global_store_dwordx2 v[194:195], v[198:199], off offset:1544
	s_mov_b64 exec, vcc
	v_lshl_add_u64 v[244:245], v[244:245], 0, s[2:3]
	v_mul_f32_e32 v116, v208, v64
	v_mul_f32_e32 v117, v209, v65
	v_mul_f32_e32 v118, v210, v66
	v_mul_f32_e32 v119, v211, v67
	v_mul_f32_e32 v120, v212, v56
	v_mul_f32_e32 v121, v213, v57
	v_mul_f32_e32 v122, v214, v58
	v_mul_f32_e32 v123, v215, v59
	v_fmac_f32_dpp v116, v64, v220 row_shr:1 row_mask:0xf bank_mask:0xf bound_ctrl:1
	v_fmac_f32_dpp v117, v65, v221 row_shr:1 row_mask:0xf bank_mask:0xf bound_ctrl:1
	v_fmac_f32_dpp v118, v66, v222 row_shr:1 row_mask:0xf bank_mask:0xf bound_ctrl:1
	v_fmac_f32_dpp v119, v67, v223 row_shr:1 row_mask:0xf bank_mask:0xf bound_ctrl:1
	v_fmac_f32_dpp v120, v56, v204 row_shr:1 row_mask:0xf bank_mask:0xf bound_ctrl:1
	v_fmac_f32_dpp v121, v57, v205 row_shr:1 row_mask:0xf bank_mask:0xf bound_ctrl:1
	v_fmac_f32_dpp v122, v58, v206 row_shr:1 row_mask:0xf bank_mask:0xf bound_ctrl:1
	v_fmac_f32_dpp v123, v59, v207 row_shr:1 row_mask:0xf bank_mask:0xf bound_ctrl:1
	v_fmac_f32_dpp v116, v64, v216 row_shl:1 row_mask:0xf bank_mask:0xf bound_ctrl:1
	v_fmac_f32_dpp v117, v65, v217 row_shl:1 row_mask:0xf bank_mask:0xf bound_ctrl:1
	v_fmac_f32_dpp v118, v66, v218 row_shl:1 row_mask:0xf bank_mask:0xf bound_ctrl:1
	v_fmac_f32_dpp v119, v67, v219 row_shl:1 row_mask:0xf bank_mask:0xf bound_ctrl:1
	v_fmac_f32_dpp v120, v56, v200 row_shl:1 row_mask:0xf bank_mask:0xf bound_ctrl:1
	v_fmac_f32_dpp v121, v57, v201 row_shl:1 row_mask:0xf bank_mask:0xf bound_ctrl:1
	v_fmac_f32_dpp v122, v58, v202 row_shl:1 row_mask:0xf bank_mask:0xf bound_ctrl:1
	v_fmac_f32_dpp v123, v59, v203 row_shl:1 row_mask:0xf bank_mask:0xf bound_ctrl:1
	v_fmac_f32_dpp v116, v68, v220 row_shl:15 row_mask:0xf bank_mask:0xf bound_ctrl:1
	v_fmac_f32_dpp v117, v69, v221 row_shl:15 row_mask:0xf bank_mask:0xf bound_ctrl:1
	v_fmac_f32_dpp v118, v70, v222 row_shl:15 row_mask:0xf bank_mask:0xf bound_ctrl:1
	v_fmac_f32_dpp v119, v71, v223 row_shl:15 row_mask:0xf bank_mask:0xf bound_ctrl:1
	v_fmac_f32_dpp v120, v60, v204 row_shl:15 row_mask:0xf bank_mask:0xf bound_ctrl:1
	v_fmac_f32_dpp v121, v61, v205 row_shl:15 row_mask:0xf bank_mask:0xf bound_ctrl:1
	v_fmac_f32_dpp v122, v62, v206 row_shl:15 row_mask:0xf bank_mask:0xf bound_ctrl:1
	v_fmac_f32_dpp v123, v63, v207 row_shl:15 row_mask:0xf bank_mask:0xf bound_ctrl:1
	v_fmac_f32_dpp v116, v44, v216 row_shr:15 row_mask:0xf bank_mask:0xf bound_ctrl:1
	v_fmac_f32_dpp v117, v45, v217 row_shr:15 row_mask:0xf bank_mask:0xf bound_ctrl:1
	v_fmac_f32_dpp v118, v46, v218 row_shr:15 row_mask:0xf bank_mask:0xf bound_ctrl:1
	v_fmac_f32_dpp v119, v47, v219 row_shr:15 row_mask:0xf bank_mask:0xf bound_ctrl:1
	v_fmac_f32_dpp v120, v36, v200 row_shr:15 row_mask:0xf bank_mask:0xf bound_ctrl:1
	v_fmac_f32_dpp v121, v37, v201 row_shr:15 row_mask:0xf bank_mask:0xf bound_ctrl:1
	v_fmac_f32_dpp v122, v38, v202 row_shr:15 row_mask:0xf bank_mask:0xf bound_ctrl:1
	v_fmac_f32_dpp v123, v39, v203 row_shr:15 row_mask:0xf bank_mask:0xf bound_ctrl:1
	v_pk_mul_f32 v[48:49], v[116:117], s[0:1]
	v_pk_mul_f32 v[50:51], v[118:119], s[0:1]
	v_pk_mul_f32 v[52:53], v[116:117], v[120:121]
	v_pk_mul_f32 v[54:55], v[118:119], v[122:123]
	v_exp_f32_e32 v48, v48
	v_exp_f32_e32 v49, v49
	v_exp_f32_e32 v50, v50
	v_exp_f32_e32 v51, v51
	s_nop 0
	v_pk_add_f32 v[48:49], v[48:49], 1.0 op_sel_hi:[1,0]
	v_pk_add_f32 v[50:51], v[50:51], 1.0 op_sel_hi:[1,0]
	v_rcp_f32_e32 v48, v48
	v_rcp_f32_e32 v49, v49
	v_rcp_f32_e32 v50, v50
	v_rcp_f32_e32 v51, v51
	s_nop 0
	v_pk_mul_f32 v[52:53], v[52:53], v[48:49]
	v_pk_mul_f32 v[54:55], v[54:55], v[50:51]
	v_cvt_pk_bf16_f32 v154, v52, v53
	v_cvt_pk_bf16_f32 v155, v54, v55
	global_store_dwordx4 v[244:245], v[152:155], off
	v_lshl_add_u64 v[244:245], v[244:245], 0, s[2:3]
	v_mul_f32_e32 v116, v208, v44
	v_mul_f32_e32 v117, v209, v45
	v_mul_f32_e32 v118, v210, v46
	v_mul_f32_e32 v119, v211, v47
	v_mul_f32_e32 v120, v212, v36
	v_mul_f32_e32 v121, v213, v37
	v_mul_f32_e32 v122, v214, v38
	v_mul_f32_e32 v123, v215, v39
	v_fmac_f32_dpp v116, v44, v220 row_shr:1 row_mask:0xf bank_mask:0xf bound_ctrl:1
	v_fmac_f32_dpp v117, v45, v221 row_shr:1 row_mask:0xf bank_mask:0xf bound_ctrl:1
	v_fmac_f32_dpp v118, v46, v222 row_shr:1 row_mask:0xf bank_mask:0xf bound_ctrl:1
	v_fmac_f32_dpp v119, v47, v223 row_shr:1 row_mask:0xf bank_mask:0xf bound_ctrl:1
	v_fmac_f32_dpp v120, v36, v204 row_shr:1 row_mask:0xf bank_mask:0xf bound_ctrl:1
	v_fmac_f32_dpp v121, v37, v205 row_shr:1 row_mask:0xf bank_mask:0xf bound_ctrl:1
	v_fmac_f32_dpp v122, v38, v206 row_shr:1 row_mask:0xf bank_mask:0xf bound_ctrl:1
	v_fmac_f32_dpp v123, v39, v207 row_shr:1 row_mask:0xf bank_mask:0xf bound_ctrl:1
	v_fmac_f32_dpp v116, v44, v216 row_shl:1 row_mask:0xf bank_mask:0xf bound_ctrl:1
	v_fmac_f32_dpp v117, v45, v217 row_shl:1 row_mask:0xf bank_mask:0xf bound_ctrl:1
	v_fmac_f32_dpp v118, v46, v218 row_shl:1 row_mask:0xf bank_mask:0xf bound_ctrl:1
	v_fmac_f32_dpp v119, v47, v219 row_shl:1 row_mask:0xf bank_mask:0xf bound_ctrl:1
	v_fmac_f32_dpp v120, v36, v200 row_shl:1 row_mask:0xf bank_mask:0xf bound_ctrl:1
	v_fmac_f32_dpp v121, v37, v201 row_shl:1 row_mask:0xf bank_mask:0xf bound_ctrl:1
	v_fmac_f32_dpp v122, v38, v202 row_shl:1 row_mask:0xf bank_mask:0xf bound_ctrl:1
	v_fmac_f32_dpp v123, v39, v203 row_shl:1 row_mask:0xf bank_mask:0xf bound_ctrl:1
	v_fmac_f32_dpp v116, v64, v220 row_shl:15 row_mask:0xf bank_mask:0xf bound_ctrl:1
	v_fmac_f32_dpp v117, v65, v221 row_shl:15 row_mask:0xf bank_mask:0xf bound_ctrl:1
	v_fmac_f32_dpp v118, v66, v222 row_shl:15 row_mask:0xf bank_mask:0xf bound_ctrl:1
	v_fmac_f32_dpp v119, v67, v223 row_shl:15 row_mask:0xf bank_mask:0xf bound_ctrl:1
	v_fmac_f32_dpp v120, v56, v204 row_shl:15 row_mask:0xf bank_mask:0xf bound_ctrl:1
	v_fmac_f32_dpp v121, v57, v205 row_shl:15 row_mask:0xf bank_mask:0xf bound_ctrl:1
	v_fmac_f32_dpp v122, v58, v206 row_shl:15 row_mask:0xf bank_mask:0xf bound_ctrl:1
	v_fmac_f32_dpp v123, v59, v207 row_shl:15 row_mask:0xf bank_mask:0xf bound_ctrl:1
	v_fmac_f32_dpp v116, v40, v216 row_shr:15 row_mask:0xf bank_mask:0xf bound_ctrl:1
	v_fmac_f32_dpp v117, v41, v217 row_shr:15 row_mask:0xf bank_mask:0xf bound_ctrl:1
	v_fmac_f32_dpp v118, v42, v218 row_shr:15 row_mask:0xf bank_mask:0xf bound_ctrl:1
	v_fmac_f32_dpp v119, v43, v219 row_shr:15 row_mask:0xf bank_mask:0xf bound_ctrl:1
	v_fmac_f32_dpp v120, v32, v200 row_shr:15 row_mask:0xf bank_mask:0xf bound_ctrl:1
	v_fmac_f32_dpp v121, v33, v201 row_shr:15 row_mask:0xf bank_mask:0xf bound_ctrl:1
	v_fmac_f32_dpp v122, v34, v202 row_shr:15 row_mask:0xf bank_mask:0xf bound_ctrl:1
	v_fmac_f32_dpp v123, v35, v203 row_shr:15 row_mask:0xf bank_mask:0xf bound_ctrl:1
	v_pk_mul_f32 v[48:49], v[116:117], s[0:1]
	v_pk_mul_f32 v[50:51], v[118:119], s[0:1]
	v_pk_mul_f32 v[52:53], v[116:117], v[120:121]
	v_pk_mul_f32 v[54:55], v[118:119], v[122:123]
	v_exp_f32_e32 v48, v48
	v_exp_f32_e32 v49, v49
	v_exp_f32_e32 v50, v50
	v_exp_f32_e32 v51, v51
	s_nop 0
	v_pk_add_f32 v[48:49], v[48:49], 1.0 op_sel_hi:[1,0]
	v_pk_add_f32 v[50:51], v[50:51], 1.0 op_sel_hi:[1,0]
	v_rcp_f32_e32 v48, v48
	v_rcp_f32_e32 v49, v49
	v_rcp_f32_e32 v50, v50
	v_rcp_f32_e32 v51, v51
	s_nop 0
	v_pk_mul_f32 v[52:53], v[52:53], v[48:49]
	v_pk_mul_f32 v[54:55], v[54:55], v[50:51]
	v_cvt_pk_bf16_f32 v150, v52, v53
	v_cvt_pk_bf16_f32 v151, v54, v55
	global_store_dwordx4 v[244:245], v[148:151], off
	v_lshl_add_u64 v[244:245], v[244:245], 0, s[2:3]
	v_mul_f32_e32 v116, v208, v40
	v_mul_f32_e32 v117, v209, v41
	v_mul_f32_e32 v118, v210, v42
	v_mul_f32_e32 v119, v211, v43
	v_mul_f32_e32 v120, v212, v32
	v_mul_f32_e32 v121, v213, v33
	v_mul_f32_e32 v122, v214, v34
	v_mul_f32_e32 v123, v215, v35
	v_fmac_f32_dpp v116, v40, v220 row_shr:1 row_mask:0xf bank_mask:0xf bound_ctrl:1
	v_fmac_f32_dpp v117, v41, v221 row_shr:1 row_mask:0xf bank_mask:0xf bound_ctrl:1
	v_fmac_f32_dpp v118, v42, v222 row_shr:1 row_mask:0xf bank_mask:0xf bound_ctrl:1
	v_fmac_f32_dpp v119, v43, v223 row_shr:1 row_mask:0xf bank_mask:0xf bound_ctrl:1
	v_fmac_f32_dpp v120, v32, v204 row_shr:1 row_mask:0xf bank_mask:0xf bound_ctrl:1
	v_fmac_f32_dpp v121, v33, v205 row_shr:1 row_mask:0xf bank_mask:0xf bound_ctrl:1
	v_fmac_f32_dpp v122, v34, v206 row_shr:1 row_mask:0xf bank_mask:0xf bound_ctrl:1
	v_fmac_f32_dpp v123, v35, v207 row_shr:1 row_mask:0xf bank_mask:0xf bound_ctrl:1
	v_fmac_f32_dpp v116, v40, v216 row_shl:1 row_mask:0xf bank_mask:0xf bound_ctrl:1
	v_fmac_f32_dpp v117, v41, v217 row_shl:1 row_mask:0xf bank_mask:0xf bound_ctrl:1
	v_fmac_f32_dpp v118, v42, v218 row_shl:1 row_mask:0xf bank_mask:0xf bound_ctrl:1
	v_fmac_f32_dpp v119, v43, v219 row_shl:1 row_mask:0xf bank_mask:0xf bound_ctrl:1
	v_fmac_f32_dpp v120, v32, v200 row_shl:1 row_mask:0xf bank_mask:0xf bound_ctrl:1
	v_fmac_f32_dpp v121, v33, v201 row_shl:1 row_mask:0xf bank_mask:0xf bound_ctrl:1
	v_fmac_f32_dpp v122, v34, v202 row_shl:1 row_mask:0xf bank_mask:0xf bound_ctrl:1
	v_fmac_f32_dpp v123, v35, v203 row_shl:1 row_mask:0xf bank_mask:0xf bound_ctrl:1
	v_fmac_f32_dpp v116, v44, v220 row_shl:15 row_mask:0xf bank_mask:0xf bound_ctrl:1
	v_fmac_f32_dpp v117, v45, v221 row_shl:15 row_mask:0xf bank_mask:0xf bound_ctrl:1
	v_fmac_f32_dpp v118, v46, v222 row_shl:15 row_mask:0xf bank_mask:0xf bound_ctrl:1
	v_fmac_f32_dpp v119, v47, v223 row_shl:15 row_mask:0xf bank_mask:0xf bound_ctrl:1
	v_fmac_f32_dpp v120, v36, v204 row_shl:15 row_mask:0xf bank_mask:0xf bound_ctrl:1
	v_fmac_f32_dpp v121, v37, v205 row_shl:15 row_mask:0xf bank_mask:0xf bound_ctrl:1
	v_fmac_f32_dpp v122, v38, v206 row_shl:15 row_mask:0xf bank_mask:0xf bound_ctrl:1
	v_fmac_f32_dpp v123, v39, v207 row_shl:15 row_mask:0xf bank_mask:0xf bound_ctrl:1
	v_pk_mul_f32 v[48:49], v[116:117], s[0:1]
	v_pk_mul_f32 v[50:51], v[118:119], s[0:1]
	v_pk_mul_f32 v[52:53], v[116:117], v[120:121]
	v_pk_mul_f32 v[54:55], v[118:119], v[122:123]
	v_exp_f32_e32 v48, v48
	v_exp_f32_e32 v49, v49
	v_exp_f32_e32 v50, v50
	v_exp_f32_e32 v51, v51
	v_cvt_pk_bf16_f32 v196, v40, v41
	v_cvt_pk_bf16_f32 v197, v42, v43
	v_cvt_pk_bf16_f32 v198, v32, v33
	v_cvt_pk_bf16_f32 v199, v34, v35
	v_pk_add_f32 v[48:49], v[48:49], 1.0 op_sel_hi:[1,0]
	v_pk_add_f32 v[50:51], v[50:51], 1.0 op_sel_hi:[1,0]
	v_rcp_f32_e32 v48, v48
	v_rcp_f32_e32 v49, v49
	v_rcp_f32_e32 v50, v50
	v_rcp_f32_e32 v51, v51
	s_nop 0
	v_pk_mul_f32 v[52:53], v[52:53], v[48:49]
	v_pk_mul_f32 v[54:55], v[54:55], v[50:51]
	v_cvt_pk_bf16_f32 v138, v52, v53
	v_cvt_pk_bf16_f32 v139, v54, v55
	s_and_saveexec_b64 vcc, s[8:9]
	global_store_dwordx4 v[244:245], v[136:139], off
	s_mov_b64 exec, vcc
	v_add_co_u32_e32 v250, vcc, 0xfffdf000, v250
	s_nop 1
	v_addc_co_u32_e32 v251, vcc, -1, v251, vcc
	v_add_co_u32_e32 v194, vcc, 0x1000, v250
	s_nop 1
	v_addc_co_u32_e32 v195, vcc, 0, v251, vcc
	s_and_saveexec_b64 vcc, s[14:15]
	global_store_dwordx2 v[250:251], v[196:197], off offset:8
	global_store_dwordx2 v[194:195], v[198:199], off offset:1544
	s_mov_b64 exec, vcc
	s_cmp_lg_u32 s83, 0
	s_cbranch_scc1 .Lup_done
	v_add_co_u32_e32 v244, vcc, 0xb0000, v246
	s_nop 1
	v_addc_co_u32_e32 v245, vcc, 0, v247, vcc
	v_add_co_u32_e32 v250, vcc, 0x16000, v248
	s_nop 1
	v_addc_co_u32_e32 v251, vcc, 0, v249, vcc
	v_add_co_u32_e32 v194, vcc, 0x1000, v250
	s_nop 1
	v_addc_co_u32_e32 v195, vcc, 0, v251, vcc
	v_mul_f32_e32 v116, v208, v28
	v_mul_f32_e32 v117, v209, v29
	v_mul_f32_e32 v118, v210, v30
	v_mul_f32_e32 v119, v211, v31
	v_mul_f32_e32 v120, v212, v20
	v_mul_f32_e32 v121, v213, v21
	v_mul_f32_e32 v122, v214, v22
	v_mul_f32_e32 v123, v215, v23
	v_fmac_f32_dpp v116, v28, v220 row_shr:1 row_mask:0xf bank_mask:0xf bound_ctrl:1
	v_fmac_f32_dpp v117, v29, v221 row_shr:1 row_mask:0xf bank_mask:0xf bound_ctrl:1
	v_fmac_f32_dpp v118, v30, v222 row_shr:1 row_mask:0xf bank_mask:0xf bound_ctrl:1
	v_fmac_f32_dpp v119, v31, v223 row_shr:1 row_mask:0xf bank_mask:0xf bound_ctrl:1
	v_fmac_f32_dpp v120, v20, v204 row_shr:1 row_mask:0xf bank_mask:0xf bound_ctrl:1
	v_fmac_f32_dpp v121, v21, v205 row_shr:1 row_mask:0xf bank_mask:0xf bound_ctrl:1
	v_fmac_f32_dpp v122, v22, v206 row_shr:1 row_mask:0xf bank_mask:0xf bound_ctrl:1
	v_fmac_f32_dpp v123, v23, v207 row_shr:1 row_mask:0xf bank_mask:0xf bound_ctrl:1
	v_fmac_f32_dpp v116, v28, v216 row_shl:1 row_mask:0xf bank_mask:0xf bound_ctrl:1
	v_fmac_f32_dpp v117, v29, v217 row_shl:1 row_mask:0xf bank_mask:0xf bound_ctrl:1
	v_fmac_f32_dpp v118, v30, v218 row_shl:1 row_mask:0xf bank_mask:0xf bound_ctrl:1
	v_fmac_f32_dpp v119, v31, v219 row_shl:1 row_mask:0xf bank_mask:0xf bound_ctrl:1
	v_fmac_f32_dpp v120, v20, v200 row_shl:1 row_mask:0xf bank_mask:0xf bound_ctrl:1
	v_fmac_f32_dpp v121, v21, v201 row_shl:1 row_mask:0xf bank_mask:0xf bound_ctrl:1
	v_fmac_f32_dpp v122, v22, v202 row_shl:1 row_mask:0xf bank_mask:0xf bound_ctrl:1
	v_fmac_f32_dpp v123, v23, v203 row_shl:1 row_mask:0xf bank_mask:0xf bound_ctrl:1
	v_fmac_f32_dpp v116, v24, v216 row_shr:15 row_mask:0xf bank_mask:0xf bound_ctrl:1
	v_fmac_f32_dpp v117, v25, v217 row_shr:15 row_mask:0xf bank_mask:0xf bound_ctrl:1
	v_fmac_f32_dpp v118, v26, v218 row_shr:15 row_mask:0xf bank_mask:0xf bound_ctrl:1
	v_fmac_f32_dpp v119, v27, v219 row_shr:15 row_mask:0xf bank_mask:0xf bound_ctrl:1
	v_fmac_f32_dpp v120, v16, v200 row_shr:15 row_mask:0xf bank_mask:0xf bound_ctrl:1
	v_fmac_f32_dpp v121, v17, v201 row_shr:15 row_mask:0xf bank_mask:0xf bound_ctrl:1
	v_fmac_f32_dpp v122, v18, v202 row_shr:15 row_mask:0xf bank_mask:0xf bound_ctrl:1
	v_fmac_f32_dpp v123, v19, v203 row_shr:15 row_mask:0xf bank_mask:0xf bound_ctrl:1
	v_pk_mul_f32 v[48:49], v[116:117], s[0:1]
	v_pk_mul_f32 v[50:51], v[118:119], s[0:1]
	v_pk_mul_f32 v[52:53], v[116:117], v[120:121]
	v_pk_mul_f32 v[54:55], v[118:119], v[122:123]
	v_exp_f32_e32 v48, v48
	v_exp_f32_e32 v49, v49
	v_exp_f32_e32 v50, v50
	v_exp_f32_e32 v51, v51
	v_cvt_pk_bf16_f32 v196, v28, v29
	v_cvt_pk_bf16_f32 v197, v30, v31
	v_cvt_pk_bf16_f32 v198, v20, v21
	v_cvt_pk_bf16_f32 v199, v22, v23
	v_pk_add_f32 v[48:49], v[48:49], 1.0 op_sel_hi:[1,0]
	v_pk_add_f32 v[50:51], v[50:51], 1.0 op_sel_hi:[1,0]
	v_rcp_f32_e32 v48, v48
	v_rcp_f32_e32 v49, v49
	v_rcp_f32_e32 v50, v50
	v_rcp_f32_e32 v51, v51
	s_nop 0
	v_pk_mul_f32 v[52:53], v[52:53], v[48:49]
	v_pk_mul_f32 v[54:55], v[54:55], v[50:51]
	v_cvt_pk_bf16_f32 v78, v52, v53
	v_cvt_pk_bf16_f32 v79, v54, v55
	s_and_saveexec_b64 vcc, s[10:11]
	global_store_dwordx4 v[244:245], v[76:79], off
	s_mov_b64 exec, vcc
	s_and_saveexec_b64 vcc, s[12:13]
	global_store_dwordx2 v[250:251], v[196:197], off offset:8
	global_store_dwordx2 v[194:195], v[198:199], off offset:1544
	s_mov_b64 exec, vcc
	v_lshl_add_u64 v[244:245], v[244:245], 0, s[2:3]
	v_mul_f32_e32 v116, v208, v24
	v_mul_f32_e32 v117, v209, v25
	v_mul_f32_e32 v118, v210, v26
	v_mul_f32_e32 v119, v211, v27
	v_mul_f32_e32 v120, v212, v16
	v_mul_f32_e32 v121, v213, v17
	v_mul_f32_e32 v122, v214, v18
	v_mul_f32_e32 v123, v215, v19
	v_fmac_f32_dpp v116, v24, v220 row_shr:1 row_mask:0xf bank_mask:0xf bound_ctrl:1
	v_fmac_f32_dpp v117, v25, v221 row_shr:1 row_mask:0xf bank_mask:0xf bound_ctrl:1
	v_fmac_f32_dpp v118, v26, v222 row_shr:1 row_mask:0xf bank_mask:0xf bound_ctrl:1
	v_fmac_f32_dpp v119, v27, v223 row_shr:1 row_mask:0xf bank_mask:0xf bound_ctrl:1
	v_fmac_f32_dpp v120, v16, v204 row_shr:1 row_mask:0xf bank_mask:0xf bound_ctrl:1
	v_fmac_f32_dpp v121, v17, v205 row_shr:1 row_mask:0xf bank_mask:0xf bound_ctrl:1
	v_fmac_f32_dpp v122, v18, v206 row_shr:1 row_mask:0xf bank_mask:0xf bound_ctrl:1
	v_fmac_f32_dpp v123, v19, v207 row_shr:1 row_mask:0xf bank_mask:0xf bound_ctrl:1
	v_fmac_f32_dpp v116, v24, v216 row_shl:1 row_mask:0xf bank_mask:0xf bound_ctrl:1
	v_fmac_f32_dpp v117, v25, v217 row_shl:1 row_mask:0xf bank_mask:0xf bound_ctrl:1
	v_fmac_f32_dpp v118, v26, v218 row_shl:1 row_mask:0xf bank_mask:0xf bound_ctrl:1
	v_fmac_f32_dpp v119, v27, v219 row_shl:1 row_mask:0xf bank_mask:0xf bound_ctrl:1
	v_fmac_f32_dpp v120, v16, v200 row_shl:1 row_mask:0xf bank_mask:0xf bound_ctrl:1
	v_fmac_f32_dpp v121, v17, v201 row_shl:1 row_mask:0xf bank_mask:0xf bound_ctrl:1
	v_fmac_f32_dpp v122, v18, v202 row_shl:1 row_mask:0xf bank_mask:0xf bound_ctrl:1
	v_fmac_f32_dpp v123, v19, v203 row_shl:1 row_mask:0xf bank_mask:0xf bound_ctrl:1
	v_fmac_f32_dpp v116, v28, v220 row_shl:15 row_mask:0xf bank_mask:0xf bound_ctrl:1
	v_fmac_f32_dpp v117, v29, v221 row_shl:15 row_mask:0xf bank_mask:0xf bound_ctrl:1
	v_fmac_f32_dpp v118, v30, v222 row_shl:15 row_mask:0xf bank_mask:0xf bound_ctrl:1
	v_fmac_f32_dpp v119, v31, v223 row_shl:15 row_mask:0xf bank_mask:0xf bound_ctrl:1
	v_fmac_f32_dpp v120, v20, v204 row_shl:15 row_mask:0xf bank_mask:0xf bound_ctrl:1
	v_fmac_f32_dpp v121, v21, v205 row_shl:15 row_mask:0xf bank_mask:0xf bound_ctrl:1
	v_fmac_f32_dpp v122, v22, v206 row_shl:15 row_mask:0xf bank_mask:0xf bound_ctrl:1
	v_fmac_f32_dpp v123, v23, v207 row_shl:15 row_mask:0xf bank_mask:0xf bound_ctrl:1
	v_fmac_f32_dpp v116, v12, v216 row_shr:15 row_mask:0xf bank_mask:0xf bound_ctrl:1
	v_fmac_f32_dpp v117, v13, v217 row_shr:15 row_mask:0xf bank_mask:0xf bound_ctrl:1
	v_fmac_f32_dpp v118, v14, v218 row_shr:15 row_mask:0xf bank_mask:0xf bound_ctrl:1
	v_fmac_f32_dpp v119, v15, v219 row_shr:15 row_mask:0xf bank_mask:0xf bound_ctrl:1
	v_fmac_f32_dpp v120, v4, v200 row_shr:15 row_mask:0xf bank_mask:0xf bound_ctrl:1
	v_fmac_f32_dpp v121, v5, v201 row_shr:15 row_mask:0xf bank_mask:0xf bound_ctrl:1
	v_fmac_f32_dpp v122, v6, v202 row_shr:15 row_mask:0xf bank_mask:0xf bound_ctrl:1
	v_fmac_f32_dpp v123, v7, v203 row_shr:15 row_mask:0xf bank_mask:0xf bound_ctrl:1
	v_pk_mul_f32 v[48:49], v[116:117], s[0:1]
	v_pk_mul_f32 v[50:51], v[118:119], s[0:1]
	v_pk_mul_f32 v[52:53], v[116:117], v[120:121]
	v_pk_mul_f32 v[54:55], v[118:119], v[122:123]
	v_exp_f32_e32 v48, v48
	v_exp_f32_e32 v49, v49
	v_exp_f32_e32 v50, v50
	v_exp_f32_e32 v51, v51
	s_nop 0
	v_pk_add_f32 v[48:49], v[48:49], 1.0 op_sel_hi:[1,0]
	v_pk_add_f32 v[50:51], v[50:51], 1.0 op_sel_hi:[1,0]
	v_rcp_f32_e32 v48, v48
	v_rcp_f32_e32 v49, v49
	v_rcp_f32_e32 v50, v50
	v_rcp_f32_e32 v51, v51
	s_nop 0
	v_pk_mul_f32 v[52:53], v[52:53], v[48:49]
	v_pk_mul_f32 v[54:55], v[54:55], v[50:51]
	v_cvt_pk_bf16_f32 v102, v52, v53
	v_cvt_pk_bf16_f32 v103, v54, v55
	global_store_dwordx4 v[244:245], v[100:103], off
	v_lshl_add_u64 v[244:245], v[244:245], 0, s[2:3]
	v_mul_f32_e32 v116, v208, v12
	v_mul_f32_e32 v117, v209, v13
	v_mul_f32_e32 v118, v210, v14
	v_mul_f32_e32 v119, v211, v15
	v_mul_f32_e32 v120, v212, v4
	v_mul_f32_e32 v121, v213, v5
	v_mul_f32_e32 v122, v214, v6
	v_mul_f32_e32 v123, v215, v7
	v_fmac_f32_dpp v116, v12, v220 row_shr:1 row_mask:0xf bank_mask:0xf bound_ctrl:1
	v_fmac_f32_dpp v117, v13, v221 row_shr:1 row_mask:0xf bank_mask:0xf bound_ctrl:1
	v_fmac_f32_dpp v118, v14, v222 row_shr:1 row_mask:0xf bank_mask:0xf bound_ctrl:1
	v_fmac_f32_dpp v119, v15, v223 row_shr:1 row_mask:0xf bank_mask:0xf bound_ctrl:1
	v_fmac_f32_dpp v120, v4, v204 row_shr:1 row_mask:0xf bank_mask:0xf bound_ctrl:1
	v_fmac_f32_dpp v121, v5, v205 row_shr:1 row_mask:0xf bank_mask:0xf bound_ctrl:1
	v_fmac_f32_dpp v122, v6, v206 row_shr:1 row_mask:0xf bank_mask:0xf bound_ctrl:1
	v_fmac_f32_dpp v123, v7, v207 row_shr:1 row_mask:0xf bank_mask:0xf bound_ctrl:1
	v_fmac_f32_dpp v116, v12, v216 row_shl:1 row_mask:0xf bank_mask:0xf bound_ctrl:1
	v_fmac_f32_dpp v117, v13, v217 row_shl:1 row_mask:0xf bank_mask:0xf bound_ctrl:1
	v_fmac_f32_dpp v118, v14, v218 row_shl:1 row_mask:0xf bank_mask:0xf bound_ctrl:1
	v_fmac_f32_dpp v119, v15, v219 row_shl:1 row_mask:0xf bank_mask:0xf bound_ctrl:1
	v_fmac_f32_dpp v120, v4, v200 row_shl:1 row_mask:0xf bank_mask:0xf bound_ctrl:1
	v_fmac_f32_dpp v121, v5, v201 row_shl:1 row_mask:0xf bank_mask:0xf bound_ctrl:1
	v_fmac_f32_dpp v122, v6, v202 row_shl:1 row_mask:0xf bank_mask:0xf bound_ctrl:1
	v_fmac_f32_dpp v123, v7, v203 row_shl:1 row_mask:0xf bank_mask:0xf bound_ctrl:1
	v_fmac_f32_dpp v116, v24, v220 row_shl:15 row_mask:0xf bank_mask:0xf bound_ctrl:1
	v_fmac_f32_dpp v117, v25, v221 row_shl:15 row_mask:0xf bank_mask:0xf bound_ctrl:1
	v_fmac_f32_dpp v118, v26, v222 row_shl:15 row_mask:0xf bank_mask:0xf bound_ctrl:1
	v_fmac_f32_dpp v119, v27, v223 row_shl:15 row_mask:0xf bank_mask:0xf bound_ctrl:1
	v_fmac_f32_dpp v120, v16, v204 row_shl:15 row_mask:0xf bank_mask:0xf bound_ctrl:1
	v_fmac_f32_dpp v121, v17, v205 row_shl:15 row_mask:0xf bank_mask:0xf bound_ctrl:1
	v_fmac_f32_dpp v122, v18, v206 row_shl:15 row_mask:0xf bank_mask:0xf bound_ctrl:1
	v_fmac_f32_dpp v123, v19, v207 row_shl:15 row_mask:0xf bank_mask:0xf bound_ctrl:1
	v_fmac_f32_dpp v116, v8, v216 row_shr:15 row_mask:0xf bank_mask:0xf bound_ctrl:1
	v_fmac_f32_dpp v117, v9, v217 row_shr:15 row_mask:0xf bank_mask:0xf bound_ctrl:1
	v_fmac_f32_dpp v118, v10, v218 row_shr:15 row_mask:0xf bank_mask:0xf bound_ctrl:1
	v_fmac_f32_dpp v119, v11, v219 row_shr:15 row_mask:0xf bank_mask:0xf bound_ctrl:1
	v_fmac_f32_dpp v120, v0, v200 row_shr:15 row_mask:0xf bank_mask:0xf bound_ctrl:1
	v_fmac_f32_dpp v121, v1, v201 row_shr:15 row_mask:0xf bank_mask:0xf bound_ctrl:1
	v_fmac_f32_dpp v122, v2, v202 row_shr:15 row_mask:0xf bank_mask:0xf bound_ctrl:1
	v_fmac_f32_dpp v123, v3, v203 row_shr:15 row_mask:0xf bank_mask:0xf bound_ctrl:1
	v_pk_mul_f32 v[48:49], v[116:117], s[0:1]
	v_pk_mul_f32 v[50:51], v[118:119], s[0:1]
	v_pk_mul_f32 v[52:53], v[116:117], v[120:121]
	v_pk_mul_f32 v[54:55], v[118:119], v[122:123]
	v_exp_f32_e32 v48, v48
	v_exp_f32_e32 v49, v49
	v_exp_f32_e32 v50, v50
	v_exp_f32_e32 v51, v51
	s_nop 0
	v_pk_add_f32 v[48:49], v[48:49], 1.0 op_sel_hi:[1,0]
	v_pk_add_f32 v[50:51], v[50:51], 1.0 op_sel_hi:[1,0]
	v_rcp_f32_e32 v48, v48
	v_rcp_f32_e32 v49, v49
	v_rcp_f32_e32 v50, v50
	v_rcp_f32_e32 v51, v51
	s_nop 0
	v_pk_mul_f32 v[52:53], v[52:53], v[48:49]
	v_pk_mul_f32 v[54:55], v[54:55], v[50:51]
	v_cvt_pk_bf16_f32 v98, v52, v53
	v_cvt_pk_bf16_f32 v99, v54, v55
	global_store_dwordx4 v[244:245], v[96:99], off
	v_lshl_add_u64 v[244:245], v[244:245], 0, s[2:3]
	v_mul_f32_e32 v116, v208, v8
	v_mul_f32_e32 v117, v209, v9
	v_mul_f32_e32 v118, v210, v10
	v_mul_f32_e32 v119, v211, v11
	v_mul_f32_e32 v120, v212, v0
	v_mul_f32_e32 v121, v213, v1
	v_mul_f32_e32 v122, v214, v2
	v_mul_f32_e32 v123, v215, v3
	v_fmac_f32_dpp v116, v8, v220 row_shr:1 row_mask:0xf bank_mask:0xf bound_ctrl:1
	v_fmac_f32_dpp v117, v9, v221 row_shr:1 row_mask:0xf bank_mask:0xf bound_ctrl:1
	v_fmac_f32_dpp v118, v10, v222 row_shr:1 row_mask:0xf bank_mask:0xf bound_ctrl:1
	v_fmac_f32_dpp v119, v11, v223 row_shr:1 row_mask:0xf bank_mask:0xf bound_ctrl:1
	v_fmac_f32_dpp v120, v0, v204 row_shr:1 row_mask:0xf bank_mask:0xf bound_ctrl:1
	v_fmac_f32_dpp v121, v1, v205 row_shr:1 row_mask:0xf bank_mask:0xf bound_ctrl:1
	v_fmac_f32_dpp v122, v2, v206 row_shr:1 row_mask:0xf bank_mask:0xf bound_ctrl:1
	v_fmac_f32_dpp v123, v3, v207 row_shr:1 row_mask:0xf bank_mask:0xf bound_ctrl:1
	v_fmac_f32_dpp v116, v8, v216 row_shl:1 row_mask:0xf bank_mask:0xf bound_ctrl:1
	v_fmac_f32_dpp v117, v9, v217 row_shl:1 row_mask:0xf bank_mask:0xf bound_ctrl:1
	v_fmac_f32_dpp v118, v10, v218 row_shl:1 row_mask:0xf bank_mask:0xf bound_ctrl:1
	v_fmac_f32_dpp v119, v11, v219 row_shl:1 row_mask:0xf bank_mask:0xf bound_ctrl:1
	v_fmac_f32_dpp v120, v0, v200 row_shl:1 row_mask:0xf bank_mask:0xf bound_ctrl:1
	v_fmac_f32_dpp v121, v1, v201 row_shl:1 row_mask:0xf bank_mask:0xf bound_ctrl:1
	v_fmac_f32_dpp v122, v2, v202 row_shl:1 row_mask:0xf bank_mask:0xf bound_ctrl:1
	v_fmac_f32_dpp v123, v3, v203 row_shl:1 row_mask:0xf bank_mask:0xf bound_ctrl:1
	v_fmac_f32_dpp v116, v12, v220 row_shl:15 row_mask:0xf bank_mask:0xf bound_ctrl:1
	v_fmac_f32_dpp v117, v13, v221 row_shl:15 row_mask:0xf bank_mask:0xf bound_ctrl:1
	v_fmac_f32_dpp v118, v14, v222 row_shl:15 row_mask:0xf bank_mask:0xf bound_ctrl:1
	v_fmac_f32_dpp v119, v15, v223 row_shl:15 row_mask:0xf bank_mask:0xf bound_ctrl:1
	v_fmac_f32_dpp v120, v4, v204 row_shl:15 row_mask:0xf bank_mask:0xf bound_ctrl:1
	v_fmac_f32_dpp v121, v5, v205 row_shl:15 row_mask:0xf bank_mask:0xf bound_ctrl:1
	v_fmac_f32_dpp v122, v6, v206 row_shl:15 row_mask:0xf bank_mask:0xf bound_ctrl:1
	v_fmac_f32_dpp v123, v7, v207 row_shl:15 row_mask:0xf bank_mask:0xf bound_ctrl:1
	v_pk_mul_f32 v[48:49], v[116:117], s[0:1]
	v_pk_mul_f32 v[50:51], v[118:119], s[0:1]
	v_pk_mul_f32 v[52:53], v[116:117], v[120:121]
	v_pk_mul_f32 v[54:55], v[118:119], v[122:123]
	v_exp_f32_e32 v48, v48
	v_exp_f32_e32 v49, v49
	v_exp_f32_e32 v50, v50
	v_exp_f32_e32 v51, v51
	v_cvt_pk_bf16_f32 v196, v8, v9
	v_cvt_pk_bf16_f32 v197, v10, v11
	v_cvt_pk_bf16_f32 v198, v0, v1
	v_cvt_pk_bf16_f32 v199, v2, v3
	v_pk_add_f32 v[48:49], v[48:49], 1.0 op_sel_hi:[1,0]
	v_pk_add_f32 v[50:51], v[50:51], 1.0 op_sel_hi:[1,0]
	v_rcp_f32_e32 v48, v48
	v_rcp_f32_e32 v49, v49
	v_rcp_f32_e32 v50, v50
	v_rcp_f32_e32 v51, v51
	s_nop 0
	v_pk_mul_f32 v[52:53], v[52:53], v[48:49]
	v_pk_mul_f32 v[54:55], v[54:55], v[50:51]
	v_cvt_pk_bf16_f32 v86, v52, v53
	v_cvt_pk_bf16_f32 v87, v54, v55
	s_and_saveexec_b64 vcc, s[8:9]
	global_store_dwordx4 v[244:245], v[84:87], off
	s_mov_b64 exec, vcc
	v_add_co_u32_e32 v250, vcc, 0xfffdf000, v250
	s_nop 1
	v_addc_co_u32_e32 v251, vcc, -1, v251, vcc
	v_add_co_u32_e32 v194, vcc, 0x1000, v250
	s_nop 1
	v_addc_co_u32_e32 v195, vcc, 0, v251, vcc
	s_and_saveexec_b64 vcc, s[14:15]
	global_store_dwordx2 v[250:251], v[196:197], off offset:8
	global_store_dwordx2 v[194:195], v[198:199], off offset:1544
	s_mov_b64 exec, vcc
